# saddr LDS-DMA in all GEMM K-loops + s_setprio toggles removed from the K-loops (both wave halves at equal priority)
# speedup vs baseline: 1.0108x; 1.0071x over previous
; #define PG8_STAGE(bufoff, gbase, voff) do { _Pragma("unroll") for (int _i = 0; _i < 2; ++_i) \
;         __builtin_amdgcn_global_load_lds((const unsigned*)((const char*)(gbase) + (voff)[_i]), (LAS unsigned*)(lds + (bufoff) + ldsw + _i * 8192), 16, 0, 0); } while (0)
; #define PG8_LDA(dst, b, h) do { _Pragma("unroll") for (int m = 0; m < 4; ++m) _Pragma("unroll") for (int k = 0; k < 2; ++k) dst[m][k] = *(const LAS bf16x8*)(lds + PG8_SA(b, h) + aoff + m * 2048 + k * 1024); } while (0)
; #define PG8_LDB(dst, b, h) do { _Pragma("unroll") for (int n = 0; n < 2; ++n) _Pragma("unroll") for (int k = 0; k < 2; ++k) dst[n][k] = *(const LAS bf16x8*)(lds + PG8_SB(b, h) + boff + n * 2048 + k * 1024); } while (0)
; #define PG8_MMA(ai, bj, At, Bt) do { __builtin_amdgcn_s_setprio(1); _Pragma("unroll") for (int m = 0; m < 4; ++m) _Pragma("unroll") for (int n = 0; n < 2; ++n) _Pragma("unroll") for (int k = 0; k < 2; ++k) \
;         acc[ai][bj][m][n] = __builtin_amdgcn_mfma_f32_16x16x32_bf16(Bt[n][k], At[m][k], acc[ai][bj][m][n], 0, 0, 0); __builtin_amdgcn_s_setprio(0); } while (0)
; #define PG8_WAIT_V(n) asm volatile("s_waitcnt vmcnt(" #n ")" ::: "memory")
; #define PG8_BAR __builtin_amdgcn_s_barrier()
; template <class Epi, class Sched, int KC, bool ALIGN_EPI = false, bool SP2 = false, bool ATILED = false>
; __device__ __forceinline__ void gemm_phase(LAS unsigned char* lds, const Gemm g, const Sched& S, const Epi& E, int wave_s) {
;     ...
;         for (int t = 0; t < nt; t += 2) {
;             const bool last = (t == nt - 2);
;             const char* a1 = cA + PG8_AOFF(t + 1);
;             const char* a2 = last ? nA : cA + PG8_AOFF(t + 2); const char* b2 = last ? nB : cB + (size_t)(t + 2) * kstep;
;             const char* a3 = a2 + kstep; const char* b3 = b2 + kstep;
;             if (last && has_next) S.a_ready(nxt);
;             if constexpr (SP2) {
;             PG8_LDB(B0, 0, 0); PG8_LDB(B1, 0, 1); PG8_SCHED; PG8_LDA(At, 0, 0); PG8_STAGE(PG8_SA(1, 1), a1 + hstepA, voffA);
;             PG8_WAIT_V(8); PG8_WAIT_L(0); PG8_BAR; PG8_MMA(0, 0, At, B0); PG8_MMA(0, 1, At, B1); PG8_BAR; PG8_SCHED;
;             PG8_LDA(At, 0, 1); PG8_STAGE(PG8_SB(0, 0), b2, voffB); PG8_STAGE(PG8_SB(0, 1), b2 + hstepB, voffB); PG8_STAGE(PG8_SA(0, 0), a2, voffA);
;             PG8_WAIT_V(8); PG8_WAIT_L(0); PG8_BAR; PG8_MMA(1, 0, At, B0); PG8_MMA(1, 1, At, B1); PG8_BAR; PG8_SCHED;
.LBB0_233:
	s_add_i32 s30, s58, 0xffc00000
	s_and_b32 s30, s30, 0x3800000
	s_and_b32 s31, s28, 0x100
	s_or_b32 s59, s31, s30
	s_and_b32 s34, s58, 0x7800000
	s_add_u32 s30, s28, 0x100
	s_addc_u32 s31, s29, 0
	s_and_b32 s35, s30, 0x100
	s_or_b32 s34, s34, s35
	s_add_u32 s34, s26, s34
	s_addc_u32 s35, s27, 0
	s_add_u32 s28, s55, s28
	s_addc_u32 s29, s56, s29
	s_add_i32 s62, 0, 0x10000
	s_cmp_eq_u32 s57, 28
	s_cselect_b32 s35, s19, s35
	s_cselect_b32 s34, s53, s34
	v_add_u32_e32 v139, s62, v163
	s_cselect_b32 s29, s17, s29
	s_cselect_b32 s28, s54, s28
	s_add_i32 s63, 0, 0x14000
	ds_read_b128 v[152:155], v139
	ds_read_b128 v[156:159], v139 offset:1024
	ds_read_b128 v[168:171], v139 offset:2048
	ds_read_b128 v[172:175], v139 offset:3072
	v_add_u32_e32 v139, s63, v163
	ds_read_b128 v[176:179], v139
	ds_read_b128 v[180:183], v139 offset:1024
	ds_read_b128 v[184:187], v139 offset:2048
	ds_read_b128 v[188:191], v139 offset:3072
	s_add_u32 s59, s26, s59
	s_addc_u32 s61, s27, 0
	s_add_u32 s60, s59, 0x10080
	s_addc_u32 s61, s61, 0
	s_add_i32 m0, s44, 0xc000
	ds_read_b128 v[198:201], v166
	ds_read_b128 v[202:205], v166 offset:1024
	ds_read_b128 v[206:209], v166 offset:2048
	ds_read_b128 v[210:213], v166 offset:3072
	ds_read_b128 v[214:217], v166 offset:4096
	ds_read_b128 v[218:221], v166 offset:5120
	ds_read_b128 v[222:225], v166 offset:6144
	ds_read_b128 v[226:229], v166 offset:7168
	global_load_lds_dwordx4 v136, s[60:61]
	s_add_i32 m0, s44, 0xe000
	s_nop 0
	global_load_lds_dwordx4 v132, s[60:61]
	s_waitcnt vmcnt(8)
	s_waitcnt lgkmcnt(0)
	s_barrier
	s_waitcnt lgkmcnt(0)
	v_mfma_f32_16x16x32_bf16 v[122:125], v[152:155], v[198:201], v[122:125]
	v_mfma_f32_16x16x32_bf16 v[114:117], v[168:171], v[198:201], v[114:117]
	v_mfma_f32_16x16x32_bf16 v[106:109], v[152:155], v[206:209], v[106:109]
	v_mfma_f32_16x16x32_bf16 v[98:101], v[168:171], v[206:209], v[98:101]
	v_mfma_f32_16x16x32_bf16 v[90:93], v[152:155], v[214:217], v[90:93]
	v_mfma_f32_16x16x32_bf16 v[82:85], v[168:171], v[214:217], v[82:85]
	v_mfma_f32_16x16x32_bf16 v[74:77], v[152:155], v[222:225], v[74:77]
	v_mfma_f32_16x16x32_bf16 v[66:69], v[168:171], v[222:225], v[66:69]
	v_mfma_f32_16x16x32_bf16 v[122:125], v[156:159], v[202:205], v[122:125]
	v_mfma_f32_16x16x32_bf16 v[114:117], v[172:175], v[202:205], v[114:117]
	v_mfma_f32_16x16x32_bf16 v[106:109], v[156:159], v[210:213], v[106:109]
	v_mfma_f32_16x16x32_bf16 v[98:101], v[172:175], v[210:213], v[98:101]
	v_mfma_f32_16x16x32_bf16 v[90:93], v[156:159], v[218:221], v[90:93]
	v_mfma_f32_16x16x32_bf16 v[82:85], v[172:175], v[218:221], v[82:85]
	v_mfma_f32_16x16x32_bf16 v[74:77], v[156:159], v[226:229], v[74:77]
	v_mfma_f32_16x16x32_bf16 v[66:69], v[172:175], v[226:229], v[66:69]
	v_mfma_f32_16x16x32_bf16 v[126:129], v[176:179], v[198:201], v[126:129]
	v_mfma_f32_16x16x32_bf16 v[118:121], v[184:187], v[198:201], v[118:121]
	v_mfma_f32_16x16x32_bf16 v[110:113], v[176:179], v[206:209], v[110:113]
	v_mfma_f32_16x16x32_bf16 v[102:105], v[184:187], v[206:209], v[102:105]
	v_mfma_f32_16x16x32_bf16 v[94:97], v[176:179], v[214:217], v[94:97]
	v_mfma_f32_16x16x32_bf16 v[86:89], v[184:187], v[214:217], v[86:89]
	v_mfma_f32_16x16x32_bf16 v[78:81], v[176:179], v[222:225], v[78:81]
	v_mfma_f32_16x16x32_bf16 v[70:73], v[184:187], v[222:225], v[70:73]
	v_mfma_f32_16x16x32_bf16 v[126:129], v[180:183], v[202:205], v[126:129]
	v_mfma_f32_16x16x32_bf16 v[118:121], v[188:191], v[202:205], v[118:121]
	v_mfma_f32_16x16x32_bf16 v[110:113], v[180:183], v[210:213], v[110:113]
	v_mfma_f32_16x16x32_bf16 v[102:105], v[188:191], v[210:213], v[102:105]
	v_mfma_f32_16x16x32_bf16 v[94:97], v[180:183], v[218:221], v[94:97]
	v_mfma_f32_16x16x32_bf16 v[86:89], v[188:191], v[218:221], v[86:89]
	v_mfma_f32_16x16x32_bf16 v[78:81], v[180:183], v[226:229], v[78:81]
	v_mfma_f32_16x16x32_bf16 v[70:73], v[188:191], v[226:229], v[70:73]
	s_barrier
	s_add_u32 s100, s34, 0x80
	s_addc_u32 s101, s35, 0
	s_add_i32 s59, s62, s38
	s_mov_b32 m0, s59
	ds_read_b128 v[198:201], v166 offset:16384
	ds_read_b128 v[202:205], v166 offset:17408
	ds_read_b128 v[206:209], v166 offset:18432
	ds_read_b128 v[210:213], v166 offset:19456
	ds_read_b128 v[214:217], v166 offset:20480
	ds_read_b128 v[218:221], v166 offset:21504
	ds_read_b128 v[222:225], v166 offset:22528
	ds_read_b128 v[226:229], v166 offset:23552
	global_load_lds_dwordx4 v134, s[28:29]
	s_add_i32 m0, s59, 0x2000
	s_add_u32 s60, s28, 0x80000
	s_addc_u32 s61, s29, 0
	s_add_i32 s59, s63, s38
	global_load_lds_dwordx4 v130, s[28:29]
	s_mov_b32 m0, s59
	s_nop 0
	global_load_lds_dwordx4 v134, s[60:61]
	s_add_i32 m0, s59, 0x2000
	s_nop 0
	global_load_lds_dwordx4 v130, s[60:61]
	s_mov_b32 m0, s44
	s_nop 0
	global_load_lds_dwordx4 v136, s[34:35]
	s_mov_b32 m0, s45
	s_nop 0
	global_load_lds_dwordx4 v132, s[34:35]
	s_waitcnt vmcnt(8)
	s_waitcnt lgkmcnt(0)
	s_barrier
; #define PG8_STAGE(bufoff, gbase, voff) do { _Pragma("unroll") for (int _i = 0; _i < 2; ++_i) \
;         __builtin_amdgcn_global_load_lds((const unsigned*)((const char*)(gbase) + (voff)[_i]), (LAS unsigned*)(lds + (bufoff) + ldsw + _i * 8192), 16, 0, 0); } while (0)
; #define PG8_LDA(dst, b, h) do { _Pragma("unroll") for (int m = 0; m < 4; ++m) _Pragma("unroll") for (int k = 0; k < 2; ++k) dst[m][k] = *(const LAS bf16x8*)(lds + PG8_SA(b, h) + aoff + m * 2048 + k * 1024); } while (0)
; #define PG8_LDB(dst, b, h) do { _Pragma("unroll") for (int n = 0; n < 2; ++n) _Pragma("unroll") for (int k = 0; k < 2; ++k) dst[n][k] = *(const LAS bf16x8*)(lds + PG8_SB(b, h) + boff + n * 2048 + k * 1024); } while (0)
; #define PG8_MMA(ai, bj, At, Bt) do { __builtin_amdgcn_s_setprio(1); _Pragma("unroll") for (int m = 0; m < 4; ++m) _Pragma("unroll") for (int n = 0; n < 2; ++n) _Pragma("unroll") for (int k = 0; k < 2; ++k) \
;         acc[ai][bj][m][n] = __builtin_amdgcn_mfma_f32_16x16x32_bf16(Bt[n][k], At[m][k], acc[ai][bj][m][n], 0, 0, 0); __builtin_amdgcn_s_setprio(0); } while (0)
; #define PG8_WAIT_V(n) asm volatile("s_waitcnt vmcnt(" #n ")" ::: "memory")
; #define PG8_WAIT_L(n) asm volatile("s_waitcnt lgkmcnt(" #n ")" ::: "memory")
; #define PG8_BAR __builtin_amdgcn_s_barrier()
; #define PG8_SCHED __builtin_amdgcn_sched_barrier(0)
; template <class Epi, class Sched, int KC, bool ALIGN_EPI = false, bool SP2 = false, bool ATILED = false>
; __device__ __forceinline__ void gemm_phase(LAS unsigned char* lds, const Gemm g, const Sched& S, const Epi& E, int wave_s) {
;     ...
;             PG8_WAIT_V(8); PG8_WAIT_L(0); PG8_BAR; PG8_MMA(1, 0, At, B0); PG8_MMA(1, 1, At, B1); PG8_BAR; PG8_SCHED;
;             PG8_LDB(B0, 1, 0); PG8_LDB(B1, 1, 1); PG8_SCHED; PG8_LDA(At, 1, 0); PG8_STAGE(PG8_SA(0, 1), a2 + hstepA, voffA);
;             PG8_WAIT_V(8); PG8_WAIT_L(0); PG8_BAR; PG8_MMA(0, 0, At, B0); PG8_MMA(0, 1, At, B1); PG8_BAR; PG8_SCHED;
	s_waitcnt lgkmcnt(0)
	v_mfma_f32_16x16x32_bf16 v[58:61], v[152:155], v[198:201], v[58:61]
	v_mfma_f32_16x16x32_bf16 v[50:53], v[168:171], v[198:201], v[50:53]
	v_mfma_f32_16x16x32_bf16 v[42:45], v[152:155], v[206:209], v[42:45]
	v_mfma_f32_16x16x32_bf16 v[34:37], v[168:171], v[206:209], v[34:37]
	v_mfma_f32_16x16x32_bf16 v[26:29], v[152:155], v[214:217], v[26:29]
	v_mfma_f32_16x16x32_bf16 v[18:21], v[168:171], v[214:217], v[18:21]
	v_mfma_f32_16x16x32_bf16 v[10:13], v[152:155], v[222:225], v[10:13]
	v_mfma_f32_16x16x32_bf16 v[6:9], v[168:171], v[222:225], v[6:9]
	v_mfma_f32_16x16x32_bf16 v[58:61], v[156:159], v[202:205], v[58:61]
	v_mfma_f32_16x16x32_bf16 v[50:53], v[172:175], v[202:205], v[50:53]
	v_mfma_f32_16x16x32_bf16 v[42:45], v[156:159], v[210:213], v[42:45]
	v_mfma_f32_16x16x32_bf16 v[34:37], v[172:175], v[210:213], v[34:37]
	v_mfma_f32_16x16x32_bf16 v[26:29], v[156:159], v[218:221], v[26:29]
	v_mfma_f32_16x16x32_bf16 v[18:21], v[172:175], v[218:221], v[18:21]
	v_mfma_f32_16x16x32_bf16 v[10:13], v[156:159], v[226:229], v[10:13]
	v_mfma_f32_16x16x32_bf16 v[6:9], v[172:175], v[226:229], v[6:9]
	v_mfma_f32_16x16x32_bf16 v[62:65], v[176:179], v[198:201], v[62:65]
	v_mfma_f32_16x16x32_bf16 v[54:57], v[184:187], v[198:201], v[54:57]
	v_mfma_f32_16x16x32_bf16 v[46:49], v[176:179], v[206:209], v[46:49]
	v_mfma_f32_16x16x32_bf16 v[38:41], v[184:187], v[206:209], v[38:41]
	v_mfma_f32_16x16x32_bf16 v[30:33], v[176:179], v[214:217], v[30:33]
	v_mfma_f32_16x16x32_bf16 v[22:25], v[184:187], v[214:217], v[22:25]
	v_mfma_f32_16x16x32_bf16 v[14:17], v[176:179], v[222:225], v[14:17]
	v_mfma_f32_16x16x32_bf16 v[2:5], v[184:187], v[222:225], v[2:5]
	v_mfma_f32_16x16x32_bf16 v[62:65], v[180:183], v[202:205], v[62:65]
	v_mfma_f32_16x16x32_bf16 v[54:57], v[188:191], v[202:205], v[54:57]
	v_mfma_f32_16x16x32_bf16 v[46:49], v[180:183], v[210:213], v[46:49]
	v_mfma_f32_16x16x32_bf16 v[38:41], v[188:191], v[210:213], v[38:41]
	v_mfma_f32_16x16x32_bf16 v[30:33], v[180:183], v[218:221], v[30:33]
	v_mfma_f32_16x16x32_bf16 v[22:25], v[188:191], v[218:221], v[22:25]
	v_mfma_f32_16x16x32_bf16 v[14:17], v[180:183], v[226:229], v[14:17]
	v_mfma_f32_16x16x32_bf16 v[2:5], v[188:191], v[226:229], v[2:5]
	s_barrier
	s_add_i32 s59, 0, 0x18000
	v_add_u32_e32 v139, s59, v163
	s_add_i32 s60, 0, 0x1c000
	ds_read_b128 v[152:155], v139
	ds_read_b128 v[156:159], v139 offset:1024
	ds_read_b128 v[168:171], v139 offset:2048
	ds_read_b128 v[172:175], v139 offset:3072
	v_add_u32_e32 v139, s60, v163
	ds_read_b128 v[176:179], v139
	ds_read_b128 v[180:183], v139 offset:1024
	ds_read_b128 v[184:187], v139 offset:2048
	ds_read_b128 v[188:191], v139 offset:3072
	s_add_u32 s34, s34, 0x10000
	s_addc_u32 s35, s35, 0
	s_mov_b32 m0, s46
	ds_read_b128 v[198:201], v166 offset:32768
	ds_read_b128 v[202:205], v166 offset:33792
	ds_read_b128 v[206:209], v166 offset:34816
	ds_read_b128 v[210:213], v166 offset:35840
	ds_read_b128 v[214:217], v166 offset:36864
	ds_read_b128 v[218:221], v166 offset:37888
	ds_read_b128 v[222:225], v166 offset:38912
	ds_read_b128 v[226:229], v166 offset:39936
	global_load_lds_dwordx4 v136, s[34:35]
	s_mov_b32 m0, s47
	s_nop 0
	global_load_lds_dwordx4 v132, s[34:35]
	s_waitcnt vmcnt(8)
	s_waitcnt lgkmcnt(0)
	s_barrier
	s_waitcnt lgkmcnt(0)
	v_mfma_f32_16x16x32_bf16 v[122:125], v[152:155], v[198:201], v[122:125]
	v_mfma_f32_16x16x32_bf16 v[114:117], v[168:171], v[198:201], v[114:117]
	v_mfma_f32_16x16x32_bf16 v[106:109], v[152:155], v[206:209], v[106:109]
	v_mfma_f32_16x16x32_bf16 v[98:101], v[168:171], v[206:209], v[98:101]
	v_mfma_f32_16x16x32_bf16 v[90:93], v[152:155], v[214:217], v[90:93]
	v_mfma_f32_16x16x32_bf16 v[82:85], v[168:171], v[214:217], v[82:85]
	v_mfma_f32_16x16x32_bf16 v[74:77], v[152:155], v[222:225], v[74:77]
	v_mfma_f32_16x16x32_bf16 v[66:69], v[168:171], v[222:225], v[66:69]
	v_mfma_f32_16x16x32_bf16 v[122:125], v[156:159], v[202:205], v[122:125]
	v_mfma_f32_16x16x32_bf16 v[114:117], v[172:175], v[202:205], v[114:117]
	v_mfma_f32_16x16x32_bf16 v[106:109], v[156:159], v[210:213], v[106:109]
	v_mfma_f32_16x16x32_bf16 v[98:101], v[172:175], v[210:213], v[98:101]
	v_mfma_f32_16x16x32_bf16 v[90:93], v[156:159], v[218:221], v[90:93]
	v_mfma_f32_16x16x32_bf16 v[82:85], v[172:175], v[218:221], v[82:85]
	v_mfma_f32_16x16x32_bf16 v[74:77], v[156:159], v[226:229], v[74:77]
	v_mfma_f32_16x16x32_bf16 v[66:69], v[172:175], v[226:229], v[66:69]
	v_mfma_f32_16x16x32_bf16 v[126:129], v[176:179], v[198:201], v[126:129]
	v_mfma_f32_16x16x32_bf16 v[118:121], v[184:187], v[198:201], v[118:121]
	v_mfma_f32_16x16x32_bf16 v[110:113], v[176:179], v[206:209], v[110:113]
	v_mfma_f32_16x16x32_bf16 v[102:105], v[184:187], v[206:209], v[102:105]
	v_mfma_f32_16x16x32_bf16 v[94:97], v[176:179], v[214:217], v[94:97]
	v_mfma_f32_16x16x32_bf16 v[86:89], v[184:187], v[214:217], v[86:89]
	v_mfma_f32_16x16x32_bf16 v[78:81], v[176:179], v[222:225], v[78:81]
	v_mfma_f32_16x16x32_bf16 v[70:73], v[184:187], v[222:225], v[70:73]
	v_mfma_f32_16x16x32_bf16 v[126:129], v[180:183], v[202:205], v[126:129]
	v_mfma_f32_16x16x32_bf16 v[118:121], v[188:191], v[202:205], v[118:121]
	v_mfma_f32_16x16x32_bf16 v[110:113], v[180:183], v[210:213], v[110:113]
	v_mfma_f32_16x16x32_bf16 v[102:105], v[188:191], v[210:213], v[102:105]
	v_mfma_f32_16x16x32_bf16 v[94:97], v[180:183], v[218:221], v[94:97]
	v_mfma_f32_16x16x32_bf16 v[86:89], v[188:191], v[218:221], v[86:89]
	v_mfma_f32_16x16x32_bf16 v[78:81], v[180:183], v[226:229], v[78:81]
	v_mfma_f32_16x16x32_bf16 v[70:73], v[188:191], v[226:229], v[70:73]
	s_barrier
; #define PG8_STAGE(bufoff, gbase, voff) do { _Pragma("unroll") for (int _i = 0; _i < 2; ++_i) \
;         __builtin_amdgcn_global_load_lds((const unsigned*)((const char*)(gbase) + (voff)[_i]), (LAS unsigned*)(lds + (bufoff) + ldsw + _i * 8192), 16, 0, 0); } while (0)
; #define PG8_LDA(dst, b, h) do { _Pragma("unroll") for (int m = 0; m < 4; ++m) _Pragma("unroll") for (int k = 0; k < 2; ++k) dst[m][k] = *(const LAS bf16x8*)(lds + PG8_SA(b, h) + aoff + m * 2048 + k * 1024); } while (0)
; #define PG8_LDB(dst, b, h) do { _Pragma("unroll") for (int n = 0; n < 2; ++n) _Pragma("unroll") for (int k = 0; k < 2; ++k) dst[n][k] = *(const LAS bf16x8*)(lds + PG8_SB(b, h) + boff + n * 2048 + k * 1024); } while (0)
; #define PG8_MMA(ai, bj, At, Bt) do { __builtin_amdgcn_s_setprio(1); _Pragma("unroll") for (int m = 0; m < 4; ++m) _Pragma("unroll") for (int n = 0; n < 2; ++n) _Pragma("unroll") for (int k = 0; k < 2; ++k) \
;         acc[ai][bj][m][n] = __builtin_amdgcn_mfma_f32_16x16x32_bf16(Bt[n][k], At[m][k], acc[ai][bj][m][n], 0, 0, 0); __builtin_amdgcn_s_setprio(0); } while (0)
; #define PG8_WAIT_V(n) asm volatile("s_waitcnt vmcnt(" #n ")" ::: "memory")
; #define PG8_WAIT_L(n) asm volatile("s_waitcnt lgkmcnt(" #n ")" ::: "memory")
; #define PG8_BAR __builtin_amdgcn_s_barrier()
; #define PG8_SCHED __builtin_amdgcn_sched_barrier(0)
; template <class Epi, class Sched, int KC, bool ALIGN_EPI = false, bool SP2 = false, bool ATILED = false>
; __device__ __forceinline__ void gemm_phase(LAS unsigned char* lds, const Gemm g, const Sched& S, const Epi& E, int wave_s) {
;     ...
;             PG8_LDB(B0, 1, 0); PG8_LDB(B1, 1, 1); PG8_SCHED; PG8_LDA(At, 1, 0); PG8_STAGE(PG8_SA(0, 1), a2 + hstepA, voffA);
;             PG8_WAIT_V(8); PG8_WAIT_L(0); PG8_BAR; PG8_MMA(0, 0, At, B0); PG8_MMA(0, 1, At, B1); PG8_BAR; PG8_SCHED;
;             PG8_LDA(At, 1, 1); PG8_STAGE(PG8_SB(1, 0), b3, voffB); PG8_STAGE(PG8_SB(1, 1), b3 + hstepB, voffB); PG8_STAGE(PG8_SA(1, 0), a3, voffA);
;             PG8_WAIT_V(8); PG8_WAIT_L(0); PG8_BAR; PG8_MMA(1, 0, At, B0); PG8_MMA(1, 1, At, B1); PG8_BAR; PG8_SCHED;
;     ...
;         if constexpr (ALIGN_EPI) { if (wr == 0) PG8_BAR; }
	s_add_u32 s98, s28, 0x80
	s_addc_u32 s99, s29, 0
	s_add_i32 s34, s59, s38
	s_mov_b32 m0, s34
	ds_read_b128 v[198:201], v166 offset:49152
	ds_read_b128 v[202:205], v166 offset:50176
	ds_read_b128 v[206:209], v166 offset:51200
	ds_read_b128 v[210:213], v166 offset:52224
	ds_read_b128 v[214:217], v166 offset:53248
	ds_read_b128 v[218:221], v166 offset:54272
	ds_read_b128 v[222:225], v166 offset:55296
	ds_read_b128 v[226:229], v166 offset:56320
	global_load_lds_dwordx4 v134, s[98:99]
	s_add_i32 m0, s34, 0x2000
	s_add_u32 s28, s28, 0x80080
	s_addc_u32 s29, s29, 0
	s_add_i32 s34, s60, s38
	global_load_lds_dwordx4 v130, s[98:99]
	s_mov_b32 m0, s34
	s_nop 0
	global_load_lds_dwordx4 v134, s[28:29]
	s_add_i32 m0, s34, 0x2000
	s_nop 0
	global_load_lds_dwordx4 v130, s[28:29]
	s_mov_b32 m0, s48
	s_nop 0
	global_load_lds_dwordx4 v136, s[100:101]
	s_mov_b32 m0, s49
	s_nop 0
	global_load_lds_dwordx4 v132, s[100:101]
	s_waitcnt vmcnt(8)
	s_waitcnt lgkmcnt(0)
	s_barrier
	s_waitcnt lgkmcnt(0)
	v_mfma_f32_16x16x32_bf16 v[58:61], v[152:155], v[198:201], v[58:61]
	v_mfma_f32_16x16x32_bf16 v[50:53], v[168:171], v[198:201], v[50:53]
	v_mfma_f32_16x16x32_bf16 v[42:45], v[152:155], v[206:209], v[42:45]
	v_mfma_f32_16x16x32_bf16 v[34:37], v[168:171], v[206:209], v[34:37]
	v_mfma_f32_16x16x32_bf16 v[26:29], v[152:155], v[214:217], v[26:29]
	v_mfma_f32_16x16x32_bf16 v[18:21], v[168:171], v[214:217], v[18:21]
	v_mfma_f32_16x16x32_bf16 v[10:13], v[152:155], v[222:225], v[10:13]
	v_mfma_f32_16x16x32_bf16 v[6:9], v[168:171], v[222:225], v[6:9]
	v_mfma_f32_16x16x32_bf16 v[58:61], v[156:159], v[202:205], v[58:61]
	v_mfma_f32_16x16x32_bf16 v[50:53], v[172:175], v[202:205], v[50:53]
	v_mfma_f32_16x16x32_bf16 v[42:45], v[156:159], v[210:213], v[42:45]
	v_mfma_f32_16x16x32_bf16 v[34:37], v[172:175], v[210:213], v[34:37]
	v_mfma_f32_16x16x32_bf16 v[26:29], v[156:159], v[218:221], v[26:29]
	v_mfma_f32_16x16x32_bf16 v[18:21], v[172:175], v[218:221], v[18:21]
	v_mfma_f32_16x16x32_bf16 v[10:13], v[156:159], v[226:229], v[10:13]
	v_mfma_f32_16x16x32_bf16 v[6:9], v[172:175], v[226:229], v[6:9]
	v_mfma_f32_16x16x32_bf16 v[62:65], v[176:179], v[198:201], v[62:65]
	v_mfma_f32_16x16x32_bf16 v[54:57], v[184:187], v[198:201], v[54:57]
	v_mfma_f32_16x16x32_bf16 v[46:49], v[176:179], v[206:209], v[46:49]
	v_mfma_f32_16x16x32_bf16 v[38:41], v[184:187], v[206:209], v[38:41]
	v_mfma_f32_16x16x32_bf16 v[30:33], v[176:179], v[214:217], v[30:33]
	v_mfma_f32_16x16x32_bf16 v[22:25], v[184:187], v[214:217], v[22:25]
	v_mfma_f32_16x16x32_bf16 v[14:17], v[176:179], v[222:225], v[14:17]
	v_mfma_f32_16x16x32_bf16 v[2:5], v[184:187], v[222:225], v[2:5]
	v_mfma_f32_16x16x32_bf16 v[62:65], v[180:183], v[202:205], v[62:65]
	v_mfma_f32_16x16x32_bf16 v[54:57], v[188:191], v[202:205], v[54:57]
	v_mfma_f32_16x16x32_bf16 v[46:49], v[180:183], v[210:213], v[46:49]
	v_mfma_f32_16x16x32_bf16 v[38:41], v[188:191], v[210:213], v[38:41]
	v_mfma_f32_16x16x32_bf16 v[30:33], v[180:183], v[218:221], v[30:33]
	v_mfma_f32_16x16x32_bf16 v[22:25], v[188:191], v[218:221], v[22:25]
	v_mfma_f32_16x16x32_bf16 v[14:17], v[180:183], v[226:229], v[14:17]
	v_mfma_f32_16x16x32_bf16 v[2:5], v[188:191], v[226:229], v[2:5]
	s_barrier
	s_add_i32 s57, s57, 2
	s_add_i32 s58, s58, 0x400000
	s_cmp_gt_u32 s57, 29
	s_mov_b64 s[28:29], s[30:31]
	s_cbranch_scc0 .LBB0_233
	s_and_b64 vcc, exec, s[14:15]
	s_cbranch_vccz .LBB0_236
	s_barrier

; #define PG8_STAGE(bufoff, gbase, voff) do { _Pragma("unroll") for (int _i = 0; _i < 2; ++_i) \
;         __builtin_amdgcn_global_load_lds((const unsigned*)((const char*)(gbase) + (voff)[_i]), (LAS unsigned*)(lds + (bufoff) + ldsw + _i * 8192), 16, 0, 0); } while (0)
; #define PG8_LDA(dst, b, h) do { _Pragma("unroll") for (int m = 0; m < 4; ++m) _Pragma("unroll") for (int k = 0; k < 2; ++k) dst[m][k] = *(const LAS bf16x8*)(lds + PG8_SA(b, h) + aoff + m * 2048 + k * 1024); } while (0)
; #define PG8_LDB(dst, b, h) do { _Pragma("unroll") for (int n = 0; n < 2; ++n) _Pragma("unroll") for (int k = 0; k < 2; ++k) dst[n][k] = *(const LAS bf16x8*)(lds + PG8_SB(b, h) + boff + n * 2048 + k * 1024); } while (0)
; #define PG8_MMA(ai, bj, At, Bt) do { __builtin_amdgcn_s_setprio(1); _Pragma("unroll") for (int m = 0; m < 4; ++m) _Pragma("unroll") for (int n = 0; n < 2; ++n) _Pragma("unroll") for (int k = 0; k < 2; ++k) \
;         acc[ai][bj][m][n] = __builtin_amdgcn_mfma_f32_16x16x32_bf16(Bt[n][k], At[m][k], acc[ai][bj][m][n], 0, 0, 0); __builtin_amdgcn_s_setprio(0); } while (0)
; #define PG8_WAIT_V(n) asm volatile("s_waitcnt vmcnt(" #n ")" ::: "memory")
; #define PG8_WAIT_L(n) asm volatile("s_waitcnt lgkmcnt(" #n ")" ::: "memory")
; template <class Epi, class Sched, int KC, bool ALIGN_EPI = false, bool SP2 = false, bool ATILED = false>
; __device__ __forceinline__ void gemm_phase(LAS unsigned char* lds, const Gemm g, const Sched& S, const Epi& E, int wave_s) {
;     ...
;             const bool last = (t == nt - 2);
;             const char* a1 = cA + PG8_AOFF(t + 1);
;             const char* a2 = last ? nA : cA + PG8_AOFF(t + 2); const char* b2 = last ? nB : cB + (size_t)(t + 2) * kstep;
;             const char* a3 = a2 + kstep; const char* b3 = b2 + kstep;
;             if (last && has_next) S.a_ready(nxt);
;             if constexpr (SP2) {
;             PG8_LDB(B0, 0, 0); PG8_LDB(B1, 0, 1); PG8_SCHED; PG8_LDA(At, 0, 0); PG8_STAGE(PG8_SA(1, 1), a1 + hstepA, voffA);
;             PG8_WAIT_V(8); PG8_WAIT_L(0); PG8_BAR; PG8_MMA(0, 0, At, B0); PG8_MMA(0, 1, At, B1); PG8_BAR; PG8_SCHED;
;             PG8_LDA(At, 0, 1); PG8_STAGE(PG8_SB(0, 0), b2, voffB); PG8_STAGE(PG8_SB(0, 1), b2 + hstepB, voffB); PG8_STAGE(PG8_SA(0, 0), a2, voffA);
;             PG8_WAIT_V(8); PG8_WAIT_L(0); PG8_BAR; PG8_MMA(1, 0, At, B0); PG8_MMA(1, 1, At, B1); PG8_BAR; PG8_SCHED;
.LBB0_318:
	s_add_u32 s8, s20, 0x100
	s_addc_u32 s9, s21, 0
	s_add_i32 s53, 0, 0x10000
	s_cmpk_eq_i32 s52, 0x54
	s_cselect_b32 s25, s17, s9
	s_cselect_b32 s24, s16, s8
	s_cselect_b32 s23, s11, s51
	s_cselect_b32 s22, s10, s50
	s_add_i32 s54, 0, 0x14000
	v_add_u32_e32 v114, s53, v249
	v_add_u32_e32 v150, s54, v249
	ds_read_b128 v[82:85], v114
	ds_read_b128 v[94:97], v114 offset:1024
	ds_read_b128 v[106:109], v114 offset:2048
	ds_read_b128 v[114:117], v114 offset:3072
	ds_read_b128 v[130:133], v150
	ds_read_b128 v[134:137], v150 offset:1024
	ds_read_b128 v[146:149], v150 offset:2048
	ds_read_b128 v[150:153], v150 offset:3072
	s_add_i32 m0, s36, 0xc000
	ds_read_b128 v[154:157], v251
	ds_read_b128 v[166:169], v251 offset:1024
	ds_read_b128 v[170:173], v251 offset:2048
	ds_read_b128 v[174:177], v251 offset:3072
	ds_read_b128 v[178:181], v251 offset:4096
	ds_read_b128 v[182:185], v251 offset:5120
	ds_read_b128 v[186:189], v251 offset:6144
	ds_read_b128 v[194:197], v251 offset:7168
	global_load_lds_dwordx4 v204, s[20:21]
	s_add_i32 m0, s36, 0xe000
	s_nop 0
	global_load_lds_dwordx4 v202, s[20:21]
	s_waitcnt vmcnt(8)
	s_waitcnt lgkmcnt(0)
	s_barrier
	s_waitcnt lgkmcnt(0)
	v_mfma_f32_16x16x32_bf16 v[162:165], v[82:85], v[154:157], v[162:165]
	v_mfma_f32_16x16x32_bf16 v[158:161], v[106:109], v[154:157], v[158:161]
	v_mfma_f32_16x16x32_bf16 v[126:129], v[82:85], v[170:173], v[126:129]
	v_mfma_f32_16x16x32_bf16 v[122:125], v[106:109], v[170:173], v[122:125]
	v_mfma_f32_16x16x32_bf16 v[102:105], v[82:85], v[178:181], v[102:105]
	v_mfma_f32_16x16x32_bf16 v[98:101], v[106:109], v[178:181], v[98:101]
	v_mfma_f32_16x16x32_bf16 v[78:81], v[82:85], v[186:189], v[78:81]
	v_mfma_f32_16x16x32_bf16 v[74:77], v[106:109], v[186:189], v[74:77]
	v_mfma_f32_16x16x32_bf16 v[162:165], v[94:97], v[166:169], v[162:165]
	v_mfma_f32_16x16x32_bf16 v[158:161], v[114:117], v[166:169], v[158:161]
	v_mfma_f32_16x16x32_bf16 v[126:129], v[94:97], v[174:177], v[126:129]
	v_mfma_f32_16x16x32_bf16 v[122:125], v[114:117], v[174:177], v[122:125]
	v_mfma_f32_16x16x32_bf16 v[102:105], v[94:97], v[182:185], v[102:105]
	v_mfma_f32_16x16x32_bf16 v[98:101], v[114:117], v[182:185], v[98:101]
	v_mfma_f32_16x16x32_bf16 v[78:81], v[94:97], v[194:197], v[78:81]
	v_mfma_f32_16x16x32_bf16 v[74:77], v[114:117], v[194:197], v[74:77]
	v_mfma_f32_16x16x32_bf16 v[142:145], v[130:133], v[154:157], v[142:145]
	v_mfma_f32_16x16x32_bf16 v[138:141], v[146:149], v[154:157], v[138:141]
	v_mfma_f32_16x16x32_bf16 v[118:121], v[130:133], v[170:173], v[118:121]
	v_mfma_f32_16x16x32_bf16 v[110:113], v[146:149], v[170:173], v[110:113]
	v_mfma_f32_16x16x32_bf16 v[90:93], v[130:133], v[178:181], v[90:93]
	v_mfma_f32_16x16x32_bf16 v[86:89], v[146:149], v[178:181], v[86:89]
	v_mfma_f32_16x16x32_bf16 v[70:73], v[130:133], v[186:189], v[70:73]
	v_mfma_f32_16x16x32_bf16 v[66:69], v[146:149], v[186:189], v[66:69]
	v_mfma_f32_16x16x32_bf16 v[142:145], v[134:137], v[166:169], v[142:145]
	v_mfma_f32_16x16x32_bf16 v[138:141], v[150:153], v[166:169], v[138:141]
	v_mfma_f32_16x16x32_bf16 v[118:121], v[134:137], v[174:177], v[118:121]
	v_mfma_f32_16x16x32_bf16 v[110:113], v[150:153], v[174:177], v[110:113]
	v_mfma_f32_16x16x32_bf16 v[90:93], v[134:137], v[182:185], v[90:93]
	v_mfma_f32_16x16x32_bf16 v[86:89], v[150:153], v[182:185], v[86:89]
	v_mfma_f32_16x16x32_bf16 v[70:73], v[134:137], v[194:197], v[70:73]
	v_mfma_f32_16x16x32_bf16 v[66:69], v[150:153], v[194:197], v[66:69]
	s_barrier
	s_add_i32 s20, s53, s35
	s_mov_b32 m0, s20
	ds_read_b128 v[154:157], v251 offset:16384
	ds_read_b128 v[166:169], v251 offset:17408
	ds_read_b128 v[170:173], v251 offset:18432
	ds_read_b128 v[174:177], v251 offset:19456
	ds_read_b128 v[178:181], v251 offset:20480
	ds_read_b128 v[182:185], v251 offset:21504
	ds_read_b128 v[186:189], v251 offset:22528
	ds_read_b128 v[194:197], v251 offset:23552
	global_load_lds_dwordx4 v0, s[22:23]
	s_add_i32 m0, s20, 0x2000
	s_add_u32 s20, s22, 0x58000
	s_addc_u32 s21, s23, 0
	s_add_i32 s53, s54, s35
	global_load_lds_dwordx4 v198, s[22:23]
	s_mov_b32 m0, s53
	s_nop 0
	global_load_lds_dwordx4 v0, s[20:21]
	s_add_i32 m0, s53, 0x2000
	s_nop 0
	global_load_lds_dwordx4 v198, s[20:21]
	s_mov_b32 m0, s36
	s_nop 0
	global_load_lds_dwordx4 v190, s[24:25]
	s_mov_b32 m0, s37
	s_nop 0
	global_load_lds_dwordx4 v192, s[24:25]
	s_waitcnt vmcnt(8)
	s_waitcnt lgkmcnt(0)
	s_barrier
	s_waitcnt lgkmcnt(0)
	v_mfma_f32_16x16x32_bf16 v[62:65], v[82:85], v[154:157], v[62:65]
	v_mfma_f32_16x16x32_bf16 v[58:61], v[106:109], v[154:157], v[58:61]
	v_mfma_f32_16x16x32_bf16 v[46:49], v[82:85], v[170:173], v[46:49]
	v_mfma_f32_16x16x32_bf16 v[42:45], v[106:109], v[170:173], v[42:45]
	v_mfma_f32_16x16x32_bf16 v[30:33], v[82:85], v[178:181], v[30:33]
	v_mfma_f32_16x16x32_bf16 v[26:29], v[106:109], v[178:181], v[26:29]
	v_mfma_f32_16x16x32_bf16 v[14:17], v[82:85], v[186:189], v[14:17]
	v_mfma_f32_16x16x32_bf16 v[10:13], v[106:109], v[186:189], v[10:13]
	v_mfma_f32_16x16x32_bf16 v[62:65], v[94:97], v[166:169], v[62:65]
	v_mfma_f32_16x16x32_bf16 v[58:61], v[114:117], v[166:169], v[58:61]
	v_mfma_f32_16x16x32_bf16 v[46:49], v[94:97], v[174:177], v[46:49]
	v_mfma_f32_16x16x32_bf16 v[42:45], v[114:117], v[174:177], v[42:45]
	v_mfma_f32_16x16x32_bf16 v[30:33], v[94:97], v[182:185], v[30:33]
	v_mfma_f32_16x16x32_bf16 v[26:29], v[114:117], v[182:185], v[26:29]
	v_mfma_f32_16x16x32_bf16 v[14:17], v[94:97], v[194:197], v[14:17]
	v_mfma_f32_16x16x32_bf16 v[10:13], v[114:117], v[194:197], v[10:13]
	v_mfma_f32_16x16x32_bf16 v[54:57], v[130:133], v[154:157], v[54:57]
	v_mfma_f32_16x16x32_bf16 v[50:53], v[146:149], v[154:157], v[50:53]
	v_mfma_f32_16x16x32_bf16 v[38:41], v[130:133], v[170:173], v[38:41]
	v_mfma_f32_16x16x32_bf16 v[34:37], v[146:149], v[170:173], v[34:37]
	v_mfma_f32_16x16x32_bf16 v[22:25], v[130:133], v[178:181], v[22:25]
	v_mfma_f32_16x16x32_bf16 v[18:21], v[146:149], v[178:181], v[18:21]
	v_mfma_f32_16x16x32_bf16 v[6:9], v[130:133], v[186:189], v[6:9]
	v_mfma_f32_16x16x32_bf16 v[2:5], v[146:149], v[186:189], v[2:5]
	v_mfma_f32_16x16x32_bf16 v[54:57], v[134:137], v[166:169], v[54:57]
	v_mfma_f32_16x16x32_bf16 v[50:53], v[150:153], v[166:169], v[50:53]
	v_mfma_f32_16x16x32_bf16 v[38:41], v[134:137], v[174:177], v[38:41]
	v_mfma_f32_16x16x32_bf16 v[34:37], v[150:153], v[174:177], v[34:37]
	v_mfma_f32_16x16x32_bf16 v[22:25], v[134:137], v[182:185], v[22:25]
	v_mfma_f32_16x16x32_bf16 v[18:21], v[150:153], v[182:185], v[18:21]
	v_mfma_f32_16x16x32_bf16 v[6:9], v[134:137], v[194:197], v[6:9]
	v_mfma_f32_16x16x32_bf16 v[2:5], v[150:153], v[194:197], v[2:5]
	s_barrier
; #define PG8_STAGE(bufoff, gbase, voff) do { _Pragma("unroll") for (int _i = 0; _i < 2; ++_i) \
;         __builtin_amdgcn_global_load_lds((const unsigned*)((const char*)(gbase) + (voff)[_i]), (LAS unsigned*)(lds + (bufoff) + ldsw + _i * 8192), 16, 0, 0); } while (0)
; #define PG8_LDA(dst, b, h) do { _Pragma("unroll") for (int m = 0; m < 4; ++m) _Pragma("unroll") for (int k = 0; k < 2; ++k) dst[m][k] = *(const LAS bf16x8*)(lds + PG8_SA(b, h) + aoff + m * 2048 + k * 1024); } while (0)
; #define PG8_LDB(dst, b, h) do { _Pragma("unroll") for (int n = 0; n < 2; ++n) _Pragma("unroll") for (int k = 0; k < 2; ++k) dst[n][k] = *(const LAS bf16x8*)(lds + PG8_SB(b, h) + boff + n * 2048 + k * 1024); } while (0)
; #define PG8_MMA(ai, bj, At, Bt) do { __builtin_amdgcn_s_setprio(1); _Pragma("unroll") for (int m = 0; m < 4; ++m) _Pragma("unroll") for (int n = 0; n < 2; ++n) _Pragma("unroll") for (int k = 0; k < 2; ++k) \
;         acc[ai][bj][m][n] = __builtin_amdgcn_mfma_f32_16x16x32_bf16(Bt[n][k], At[m][k], acc[ai][bj][m][n], 0, 0, 0); __builtin_amdgcn_s_setprio(0); } while (0)
; #define PG8_WAIT_V(n) asm volatile("s_waitcnt vmcnt(" #n ")" ::: "memory")
; #define PG8_WAIT_L(n) asm volatile("s_waitcnt lgkmcnt(" #n ")" ::: "memory")
; #define PG8_BAR __builtin_amdgcn_s_barrier()
; #define PG8_SCHED __builtin_amdgcn_sched_barrier(0)
; template <class Epi, class Sched, int KC, bool ALIGN_EPI = false, bool SP2 = false, bool ATILED = false>
; __device__ __forceinline__ void gemm_phase(LAS unsigned char* lds, const Gemm g, const Sched& S, const Epi& E, int wave_s) {
;     ...
;             PG8_LDB(B0, 1, 0); PG8_LDB(B1, 1, 1); PG8_SCHED; PG8_LDA(At, 1, 0); PG8_STAGE(PG8_SA(0, 1), a2 + hstepA, voffA);
;             PG8_WAIT_V(8); PG8_WAIT_L(0); PG8_BAR; PG8_MMA(0, 0, At, B0); PG8_MMA(0, 1, At, B1); PG8_BAR; PG8_SCHED;
;             PG8_LDA(At, 1, 1); PG8_STAGE(PG8_SB(1, 0), b3, voffB); PG8_STAGE(PG8_SB(1, 1), b3 + hstepB, voffB); PG8_STAGE(PG8_SA(1, 0), a3, voffA);
;             PG8_WAIT_V(8); PG8_WAIT_L(0); PG8_BAR; PG8_MMA(1, 0, At, B0); PG8_MMA(1, 1, At, B1); PG8_BAR; PG8_SCHED;
	s_add_i32 s53, 0, 0x18000
	s_add_i32 s54, 0, 0x1c000
	v_add_u32_e32 v114, s53, v249
	v_add_u32_e32 v150, s54, v249
	ds_read_b128 v[82:85], v114
	ds_read_b128 v[94:97], v114 offset:1024
	ds_read_b128 v[106:109], v114 offset:2048
	ds_read_b128 v[114:117], v114 offset:3072
	ds_read_b128 v[130:133], v150
	ds_read_b128 v[134:137], v150 offset:1024
	ds_read_b128 v[146:149], v150 offset:2048
	ds_read_b128 v[150:153], v150 offset:3072
	s_add_u32 s20, s24, 0x160000
	s_addc_u32 s21, s25, 0
	s_mov_b32 m0, s38
	ds_read_b128 v[154:157], v251 offset:32768
	ds_read_b128 v[166:169], v251 offset:33792
	ds_read_b128 v[170:173], v251 offset:34816
	ds_read_b128 v[174:177], v251 offset:35840
	ds_read_b128 v[178:181], v251 offset:36864
	ds_read_b128 v[182:185], v251 offset:37888
	ds_read_b128 v[186:189], v251 offset:38912
	ds_read_b128 v[194:197], v251 offset:39936
	global_load_lds_dwordx4 v190, s[20:21]
	s_mov_b32 m0, s39
	s_nop 0
	global_load_lds_dwordx4 v192, s[20:21]
	s_waitcnt vmcnt(8)
	s_waitcnt lgkmcnt(0)
	s_barrier
	s_waitcnt lgkmcnt(0)
	v_mfma_f32_16x16x32_bf16 v[162:165], v[82:85], v[154:157], v[162:165]
	v_mfma_f32_16x16x32_bf16 v[158:161], v[106:109], v[154:157], v[158:161]
	v_mfma_f32_16x16x32_bf16 v[126:129], v[82:85], v[170:173], v[126:129]
	v_mfma_f32_16x16x32_bf16 v[122:125], v[106:109], v[170:173], v[122:125]
	v_mfma_f32_16x16x32_bf16 v[102:105], v[82:85], v[178:181], v[102:105]
	v_mfma_f32_16x16x32_bf16 v[98:101], v[106:109], v[178:181], v[98:101]
	v_mfma_f32_16x16x32_bf16 v[78:81], v[82:85], v[186:189], v[78:81]
	v_mfma_f32_16x16x32_bf16 v[74:77], v[106:109], v[186:189], v[74:77]
	v_mfma_f32_16x16x32_bf16 v[162:165], v[94:97], v[166:169], v[162:165]
	v_mfma_f32_16x16x32_bf16 v[158:161], v[114:117], v[166:169], v[158:161]
	v_mfma_f32_16x16x32_bf16 v[126:129], v[94:97], v[174:177], v[126:129]
	v_mfma_f32_16x16x32_bf16 v[122:125], v[114:117], v[174:177], v[122:125]
	v_mfma_f32_16x16x32_bf16 v[102:105], v[94:97], v[182:185], v[102:105]
	v_mfma_f32_16x16x32_bf16 v[98:101], v[114:117], v[182:185], v[98:101]
	v_mfma_f32_16x16x32_bf16 v[78:81], v[94:97], v[194:197], v[78:81]
	v_mfma_f32_16x16x32_bf16 v[74:77], v[114:117], v[194:197], v[74:77]
	v_mfma_f32_16x16x32_bf16 v[142:145], v[130:133], v[154:157], v[142:145]
	v_mfma_f32_16x16x32_bf16 v[138:141], v[146:149], v[154:157], v[138:141]
	v_mfma_f32_16x16x32_bf16 v[118:121], v[130:133], v[170:173], v[118:121]
	v_mfma_f32_16x16x32_bf16 v[110:113], v[146:149], v[170:173], v[110:113]
	v_mfma_f32_16x16x32_bf16 v[90:93], v[130:133], v[178:181], v[90:93]
	v_mfma_f32_16x16x32_bf16 v[86:89], v[146:149], v[178:181], v[86:89]
	v_mfma_f32_16x16x32_bf16 v[70:73], v[130:133], v[186:189], v[70:73]
	v_mfma_f32_16x16x32_bf16 v[66:69], v[146:149], v[186:189], v[66:69]
	v_mfma_f32_16x16x32_bf16 v[142:145], v[134:137], v[166:169], v[142:145]
	v_mfma_f32_16x16x32_bf16 v[138:141], v[150:153], v[166:169], v[138:141]
	v_mfma_f32_16x16x32_bf16 v[118:121], v[134:137], v[174:177], v[118:121]
	v_mfma_f32_16x16x32_bf16 v[110:113], v[150:153], v[174:177], v[110:113]
	v_mfma_f32_16x16x32_bf16 v[90:93], v[134:137], v[182:185], v[90:93]
	v_mfma_f32_16x16x32_bf16 v[86:89], v[150:153], v[182:185], v[86:89]
	v_mfma_f32_16x16x32_bf16 v[70:73], v[134:137], v[194:197], v[70:73]
	v_mfma_f32_16x16x32_bf16 v[66:69], v[150:153], v[194:197], v[66:69]
	s_barrier
	s_add_u32 s98, s22, 0x80
	s_addc_u32 s99, s23, 0
	s_add_u32 s100, s24, 0x80
	s_addc_u32 s101, s25, 0
	s_add_i32 s20, s53, s35
	s_mov_b32 m0, s20
	ds_read_b128 v[154:157], v251 offset:49152
	ds_read_b128 v[166:169], v251 offset:50176
	ds_read_b128 v[170:173], v251 offset:51200
	ds_read_b128 v[174:177], v251 offset:52224
	ds_read_b128 v[178:181], v251 offset:53248
	ds_read_b128 v[182:185], v251 offset:54272
	ds_read_b128 v[186:189], v251 offset:55296
	ds_read_b128 v[194:197], v251 offset:56320
	global_load_lds_dwordx4 v0, s[98:99]
	s_add_i32 m0, s20, 0x2000
	s_add_u32 s20, s22, 0x58080
	s_addc_u32 s21, s23, 0
	s_add_i32 s22, s54, s35
	global_load_lds_dwordx4 v198, s[98:99]
	s_mov_b32 m0, s22
	s_nop 0
	global_load_lds_dwordx4 v0, s[20:21]
	s_add_i32 m0, s22, 0x2000
	s_nop 0
	global_load_lds_dwordx4 v198, s[20:21]
	s_mov_b32 m0, s43
	s_nop 0
	global_load_lds_dwordx4 v190, s[100:101]
	s_mov_b32 m0, s44
	s_nop 0
	global_load_lds_dwordx4 v192, s[100:101]
	s_waitcnt vmcnt(8)
	s_waitcnt lgkmcnt(0)
	s_barrier
; #define GAS __attribute__((address_space(1)))
;     DI void operator()(const f32x4 (&acc)[2][2][4][2], const Unit& u, int wr, int wc, int fr, int fq) const {
;         const int row0 = u.pm * BM + wr * 64 + fr, col0 = u.pn * BM + wc * 64 + 8 * fq;
;         const size_t hbase = (size_t)u.pn * ((size_t)M * 256) + wc * 64 + 8 * fq;
;         u32x4 H[2][4][2];
; #pragma unroll
;         for (int ai = 0; ai < 2; ++ai)
; #pragma unroll
;             for (int m = 0; m < 4; ++m)
; #pragma unroll
;                 for (int bj = 0; bj < 2; ++bj) H[ai][m][bj] = *(const GAS u32x4*)(hi + hbase + (size_t)(row0 + ai * HALF + m * 16) * 256 + bj * 32);
;         asm volatile("" ::: "memory");
; #pragma unroll
;         for (int ai = 0; ai < 2; ++ai) {
; #pragma unroll
;             for (int m = 0; m < 4; ++m) {
;                 const int r = row0 + ai * HALF + m * 16; const size_t off = (size_t)r * DM + col0; float ss = 0.f;
; #pragma unroll
;                 for (int bj = 0; bj < 2; ++bj) {
;                     const u32x4 h = H[ai][m][bj];
;                     const f32x4 a0 = acc[ai][bj][m][0], a1 = acc[ai][bj][m][1];
;                     float v[8];
;                     v[0] = bflo(h.x) + a0[0] * scale; v[1] = bfhi(h.x) + a0[1] * scale;
;                     v[2] = bflo(h.y) + a0[2] * scale; v[3] = bfhi(h.y) + a0[3] * scale;
;                     v[4] = bflo(h.z) + a1[0] * scale; v[5] = bfhi(h.z) + a1[1] * scale;
;                     v[6] = bflo(h.w) + a1[2] * scale; v[7] = bfhi(h.w) + a1[3] * scale;
; #pragma unroll
;                     for (int e = 0; e < 8; ++e) ss += v[e] * v[e];
;                     u32x4 nh;
;                     nh.x = cvtpk(v[0], v[1]); nh.y = cvtpk(v[2], v[3]); nh.z = cvtpk(v[4], v[5]); nh.w = cvtpk(v[6], v[7]);
;                     *(GAS u32x4*)(hi + hbase + (size_t)r * 256 + bj * 32) = nh;
;                     if (out) { *(GAS f32x4*)(out + off + bj * 32) = (f32x4){v[0], v[1], v[2], v[3]}; *(GAS f32x4*)(out + off + bj * 32 + 4) = (f32x4){v[4], v[5], v[6], v[7]}; }
; template <class Epi, class Sched, int KC, bool ALIGN_EPI = false, bool SP2 = false, bool ATILED = false>
; __device__ __forceinline__ void gemm_phase(LAS unsigned char* lds, const Gemm g, const Sched& S, const Epi& E, int wave_s) {
;     ...
;             PG8_WAIT_V(8); PG8_WAIT_L(0); PG8_BAR; PG8_MMA(1, 0, At, B0); PG8_MMA(1, 1, At, B1); PG8_BAR; PG8_SCHED;
	s_waitcnt lgkmcnt(0)
	v_mfma_f32_16x16x32_bf16 v[62:65], v[82:85], v[154:157], v[62:65]
	v_mfma_f32_16x16x32_bf16 v[58:61], v[106:109], v[154:157], v[58:61]
	v_mfma_f32_16x16x32_bf16 v[46:49], v[82:85], v[170:173], v[46:49]
	v_mfma_f32_16x16x32_bf16 v[42:45], v[106:109], v[170:173], v[42:45]
	v_mfma_f32_16x16x32_bf16 v[30:33], v[82:85], v[178:181], v[30:33]
	v_mfma_f32_16x16x32_bf16 v[26:29], v[106:109], v[178:181], v[26:29]
	v_mfma_f32_16x16x32_bf16 v[14:17], v[82:85], v[186:189], v[14:17]
	v_mfma_f32_16x16x32_bf16 v[10:13], v[106:109], v[186:189], v[10:13]
	v_mfma_f32_16x16x32_bf16 v[62:65], v[94:97], v[166:169], v[62:65]
	v_mfma_f32_16x16x32_bf16 v[58:61], v[114:117], v[166:169], v[58:61]
	v_mfma_f32_16x16x32_bf16 v[46:49], v[94:97], v[174:177], v[46:49]
	v_mfma_f32_16x16x32_bf16 v[42:45], v[114:117], v[174:177], v[42:45]
	v_mfma_f32_16x16x32_bf16 v[30:33], v[94:97], v[182:185], v[30:33]
	v_mfma_f32_16x16x32_bf16 v[26:29], v[114:117], v[182:185], v[26:29]
	v_mfma_f32_16x16x32_bf16 v[14:17], v[94:97], v[194:197], v[14:17]
	v_mfma_f32_16x16x32_bf16 v[10:13], v[114:117], v[194:197], v[10:13]
	v_mfma_f32_16x16x32_bf16 v[54:57], v[130:133], v[154:157], v[54:57]
	v_mfma_f32_16x16x32_bf16 v[50:53], v[146:149], v[154:157], v[50:53]
	v_mfma_f32_16x16x32_bf16 v[38:41], v[130:133], v[170:173], v[38:41]
	v_mfma_f32_16x16x32_bf16 v[34:37], v[146:149], v[170:173], v[34:37]
	v_mfma_f32_16x16x32_bf16 v[22:25], v[130:133], v[178:181], v[22:25]
	v_mfma_f32_16x16x32_bf16 v[18:21], v[146:149], v[178:181], v[18:21]
	v_mfma_f32_16x16x32_bf16 v[6:9], v[130:133], v[186:189], v[6:9]
	v_mfma_f32_16x16x32_bf16 v[2:5], v[146:149], v[186:189], v[2:5]
	v_mfma_f32_16x16x32_bf16 v[54:57], v[134:137], v[166:169], v[54:57]
	v_mfma_f32_16x16x32_bf16 v[50:53], v[150:153], v[166:169], v[50:53]
	v_mfma_f32_16x16x32_bf16 v[38:41], v[134:137], v[174:177], v[38:41]
	v_mfma_f32_16x16x32_bf16 v[34:37], v[150:153], v[174:177], v[34:37]
	v_mfma_f32_16x16x32_bf16 v[22:25], v[134:137], v[182:185], v[22:25]
	v_mfma_f32_16x16x32_bf16 v[18:21], v[150:153], v[182:185], v[18:21]
	v_mfma_f32_16x16x32_bf16 v[6:9], v[134:137], v[194:197], v[6:9]
	v_mfma_f32_16x16x32_bf16 v[2:5], v[150:153], v[194:197], v[2:5]
	s_barrier
	s_add_i32 s52, s52, 2
	s_add_u32 s50, s50, 0x100
	s_addc_u32 s51, s51, 0
	s_cmpk_gt_u32 s52, 0x55
	s_mov_b64 s[20:21], s[8:9]
	s_cbranch_scc0 .LBB0_318
	v_lshl_add_u32 v206, s19, 8, v248
	s_ashr_i32 s19, s18, 31
	s_lshl_b64 s[8:9], s[18:19], 23
	v_ashrrev_i32_e32 v207, 31, v206
	v_or_b32_e32 v236, 16, v206
	v_lshl_add_u64 v[82:83], v[200:201], 0, s[8:9]
	v_lshlrev_b64 v[84:85], 9, v[206:207]
	v_ashrrev_i32_e32 v237, 31, v236
	v_or_b32_e32 v232, 32, v206
	v_lshl_add_u64 v[238:239], v[82:83], 0, v[84:85]
	v_lshlrev_b64 v[84:85], 9, v[236:237]
	v_ashrrev_i32_e32 v233, 31, v232
	v_or_b32_e32 v228, 48, v206
	v_lshl_add_u64 v[234:235], v[82:83], 0, v[84:85]
	v_lshlrev_b64 v[84:85], 9, v[232:233]
	v_ashrrev_i32_e32 v229, 31, v228
	v_add_u32_e32 v224, 0x80, v206
	v_lshl_add_u64 v[230:231], v[82:83], 0, v[84:85]
	v_lshlrev_b64 v[84:85], 9, v[228:229]
	v_ashrrev_i32_e32 v225, 31, v224
	v_add_u32_e32 v220, 0x90, v206
	global_load_dwordx4 v[194:197], v[238:239], off
	global_load_dwordx4 v[186:189], v[238:239], off offset:64
	v_lshl_add_u64 v[226:227], v[82:83], 0, v[84:85]
	v_lshlrev_b64 v[84:85], 9, v[224:225]
	v_ashrrev_i32_e32 v221, 31, v220
	v_add_u32_e32 v216, 0xa0, v206
	v_lshl_add_u64 v[222:223], v[82:83], 0, v[84:85]
	v_lshlrev_b64 v[84:85], 9, v[220:221]
	v_ashrrev_i32_e32 v217, 31, v216
	v_add_u32_e32 v210, 0xb0, v206
	v_lshl_add_u64 v[218:219], v[82:83], 0, v[84:85]
	v_lshlrev_b64 v[84:85], 9, v[216:217]
	v_ashrrev_i32_e32 v211, 31, v210
	v_lshl_add_u64 v[214:215], v[82:83], 0, v[84:85]
	v_lshlrev_b64 v[84:85], 9, v[210:211]
	v_lshl_add_u64 v[208:209], v[82:83], 0, v[84:85]
	global_load_dwordx4 v[182:185], v[234:235], off
	global_load_dwordx4 v[178:181], v[234:235], off offset:64
	global_load_dwordx4 v[174:177], v[230:231], off
	global_load_dwordx4 v[170:173], v[230:231], off offset:64
	global_load_dwordx4 v[166:169], v[226:227], off
	global_load_dwordx4 v[154:157], v[226:227], off offset:64
	global_load_dwordx4 v[150:153], v[222:223], off
	global_load_dwordx4 v[146:149], v[222:223], off offset:64
	global_load_dwordx4 v[134:137], v[218:219], off
	global_load_dwordx4 v[130:133], v[218:219], off offset:64
	global_load_dwordx4 v[114:117], v[214:215], off
	global_load_dwordx4 v[106:109], v[214:215], off offset:64
	global_load_dwordx4 v[94:97], v[208:209], off
	global_load_dwordx4 v[82:85], v[208:209], off offset:64
	v_lshl_or_b32 v212, s18, 8, v250
	v_ashrrev_i32_e32 v213, 31, v212
	v_lshlrev_b64 v[240:241], 11, v[206:207]
	v_lshl_add_u64 v[240:241], v[240:241], 0, v[212:213]
	s_andn2_b64 vcc, exec, s[14:15]
	v_lshl_add_u64 v[240:241], v[240:241], 2, s[12:13]
	s_waitcnt vmcnt(0)
	v_lshlrev_b32_e32 v252, 16, v194
	v_and_b32_e32 v253, 0xffff0000, v194
	v_lshlrev_b32_e32 v194, 16, v195
	v_and_b32_e32 v195, 0xffff0000, v195
	v_pk_fma_f32 v[164:165], v[164:165], 0.5, v[194:195] op_sel_hi:[1,0,1]
	v_lshlrev_b32_e32 v194, 16, v196
	v_and_b32_e32 v195, 0xffff0000, v196
	v_pk_fma_f32 v[158:159], v[158:159], 0.5, v[194:195] op_sel_hi:[1,0,1]
	v_lshlrev_b32_e32 v194, 16, v197
	v_and_b32_e32 v195, 0xffff0000, v197
	v_pk_fma_f32 v[162:163], v[162:163], 0.5, v[252:253] op_sel_hi:[1,0,1]
	v_pk_fma_f32 v[160:161], v[160:161], 0.5, v[194:195] op_sel_hi:[1,0,1]
	v_cvt_pk_bf16_f32 v194, v162, v163
	v_cvt_pk_bf16_f32 v195, v164, v165
	v_cvt_pk_bf16_f32 v196, v158, v159
	s_nop 0
	v_cvt_pk_bf16_f32 v197, v160, v161
	global_store_dwordx4 v[238:239], v[194:197], off
	s_nop 1
	v_cndmask_b32_e64 v194, 0, 1, s[14:15]
	v_cmp_ne_u32_e64 s[8:9], 1, v194
	s_cbranch_vccnz .LBB0_321
	global_store_dwordx4 v[240:241], v[162:165], off
	global_store_dwordx4 v[240:241], v[158:161], off offset:16

; #define PG8_STAGE(bufoff, gbase, voff) do { _Pragma("unroll") for (int _i = 0; _i < 2; ++_i) \
;         __builtin_amdgcn_global_load_lds((const unsigned*)((const char*)(gbase) + (voff)[_i]), (LAS unsigned*)(lds + (bufoff) + ldsw + _i * 8192), 16, 0, 0); } while (0)
; #define PG8_LDA(dst, b, h) do { _Pragma("unroll") for (int m = 0; m < 4; ++m) _Pragma("unroll") for (int k = 0; k < 2; ++k) dst[m][k] = *(const LAS bf16x8*)(lds + PG8_SA(b, h) + aoff + m * 2048 + k * 1024); } while (0)
; #define PG8_LDB(dst, b, h) do { _Pragma("unroll") for (int n = 0; n < 2; ++n) _Pragma("unroll") for (int k = 0; k < 2; ++k) dst[n][k] = *(const LAS bf16x8*)(lds + PG8_SB(b, h) + boff + n * 2048 + k * 1024); } while (0)
; #define PG8_MMA(ai, bj, At, Bt) do { __builtin_amdgcn_s_setprio(1); _Pragma("unroll") for (int m = 0; m < 4; ++m) _Pragma("unroll") for (int n = 0; n < 2; ++n) _Pragma("unroll") for (int k = 0; k < 2; ++k) \
;         acc[ai][bj][m][n] = __builtin_amdgcn_mfma_f32_16x16x32_bf16(Bt[n][k], At[m][k], acc[ai][bj][m][n], 0, 0, 0); __builtin_amdgcn_s_setprio(0); } while (0)
; #define PG8_WAIT_V(n) asm volatile("s_waitcnt vmcnt(" #n ")" ::: "memory")
; #define PG8_BAR __builtin_amdgcn_s_barrier()
; template <class Epi, class Sched, int KC, bool ALIGN_EPI = false, bool SP2 = false, bool ATILED = false>
; __device__ __forceinline__ void gemm_phase(LAS unsigned char* lds, const Gemm g, const Sched& S, const Epi& E, int wave_s) {
;     ...
;         for (int t = 0; t < nt; t += 2) {
;             const bool last = (t == nt - 2);
;             const char* a1 = cA + PG8_AOFF(t + 1);
;             const char* a2 = last ? nA : cA + PG8_AOFF(t + 2); const char* b2 = last ? nB : cB + (size_t)(t + 2) * kstep;
;             const char* a3 = a2 + kstep; const char* b3 = b2 + kstep;
;             if (last && has_next) S.a_ready(nxt);
;             if constexpr (SP2) {
;             PG8_LDB(B0, 0, 0); PG8_LDB(B1, 0, 1); PG8_SCHED; PG8_LDA(At, 0, 0); PG8_STAGE(PG8_SA(1, 1), a1 + hstepA, voffA);
;             PG8_WAIT_V(8); PG8_WAIT_L(0); PG8_BAR; PG8_MMA(0, 0, At, B0); PG8_MMA(0, 1, At, B1); PG8_BAR; PG8_SCHED;
;             PG8_LDA(At, 0, 1); PG8_STAGE(PG8_SB(0, 0), b2, voffB); PG8_STAGE(PG8_SB(0, 1), b2 + hstepB, voffB); PG8_STAGE(PG8_SA(0, 0), a2, voffA);
;             PG8_WAIT_V(8); PG8_WAIT_L(0); PG8_BAR; PG8_MMA(1, 0, At, B0); PG8_MMA(1, 1, At, B1); PG8_BAR; PG8_SCHED;
.LBB0_430:
	s_add_i32 s30, s66, 0xffc00000
	s_and_b32 s30, s30, 0x3800000
	s_and_b32 s31, s28, 0x100
	s_or_b32 s67, s31, s30
	s_and_b32 s34, s66, 0x7800000
	s_add_u32 s30, s28, 0x100
	s_addc_u32 s31, s29, 0
	s_and_b32 s35, s30, 0x100
	s_or_b32 s34, s34, s35
	s_add_u32 s34, s26, s34
	s_addc_u32 s35, s27, 0
	s_add_u32 s28, s63, s28
	s_addc_u32 s29, s64, s29
	s_add_i32 s70, 0, 0x10000
	s_cmp_eq_u32 s65, 28
	s_cselect_b32 s35, s19, s35
	s_cselect_b32 s34, s61, s34
	v_add_u32_e32 v139, s70, v165
	s_cselect_b32 s29, s17, s29
	s_cselect_b32 s28, s62, s28
	s_add_i32 s71, 0, 0x14000
	ds_read_b128 v[152:155], v139
	ds_read_b128 v[160:163], v139 offset:1024
	ds_read_b128 v[174:177], v139 offset:2048
	ds_read_b128 v[178:181], v139 offset:3072
	v_add_u32_e32 v139, s71, v165
	ds_read_b128 v[182:185], v139
	ds_read_b128 v[186:189], v139 offset:1024
	ds_read_b128 v[190:193], v139 offset:2048
	ds_read_b128 v[194:197], v139 offset:3072
	s_add_u32 s67, s26, s67
	s_addc_u32 s69, s27, 0
	s_add_u32 s68, s67, 0x10080
	s_addc_u32 s69, s69, 0
	s_add_i32 m0, s25, 0xc000
	ds_read_b128 v[198:201], v173
	ds_read_b128 v[202:205], v173 offset:1024
	ds_read_b128 v[206:209], v173 offset:2048
	ds_read_b128 v[210:213], v173 offset:3072
	ds_read_b128 v[214:217], v173 offset:4096
	ds_read_b128 v[218:221], v173 offset:5120
	ds_read_b128 v[222:225], v173 offset:6144
	ds_read_b128 v[226:229], v173 offset:7168
	global_load_lds_dwordx4 v136, s[68:69]
	s_add_i32 m0, s25, 0xe000
	s_nop 0
	global_load_lds_dwordx4 v132, s[68:69]
	s_waitcnt vmcnt(8)
	s_waitcnt lgkmcnt(0)
	s_barrier
	s_waitcnt lgkmcnt(0)
	v_mfma_f32_16x16x32_bf16 v[126:129], v[152:155], v[198:201], v[126:129]
	v_mfma_f32_16x16x32_bf16 v[122:125], v[174:177], v[198:201], v[122:125]
	v_mfma_f32_16x16x32_bf16 v[114:117], v[152:155], v[206:209], v[114:117]
	v_mfma_f32_16x16x32_bf16 v[106:109], v[174:177], v[206:209], v[106:109]
	v_mfma_f32_16x16x32_bf16 v[98:101], v[152:155], v[214:217], v[98:101]
	v_mfma_f32_16x16x32_bf16 v[90:93], v[174:177], v[214:217], v[90:93]
	v_mfma_f32_16x16x32_bf16 v[82:85], v[152:155], v[222:225], v[82:85]
	v_mfma_f32_16x16x32_bf16 v[74:77], v[174:177], v[222:225], v[74:77]
	v_mfma_f32_16x16x32_bf16 v[126:129], v[160:163], v[202:205], v[126:129]
	v_mfma_f32_16x16x32_bf16 v[122:125], v[178:181], v[202:205], v[122:125]
	v_mfma_f32_16x16x32_bf16 v[114:117], v[160:163], v[210:213], v[114:117]
	v_mfma_f32_16x16x32_bf16 v[106:109], v[178:181], v[210:213], v[106:109]
	v_mfma_f32_16x16x32_bf16 v[98:101], v[160:163], v[218:221], v[98:101]
	v_mfma_f32_16x16x32_bf16 v[90:93], v[178:181], v[218:221], v[90:93]
	v_mfma_f32_16x16x32_bf16 v[82:85], v[160:163], v[226:229], v[82:85]
	v_mfma_f32_16x16x32_bf16 v[74:77], v[178:181], v[226:229], v[74:77]
	v_mfma_f32_16x16x32_bf16 v[118:121], v[182:185], v[198:201], v[118:121]
	v_mfma_f32_16x16x32_bf16 v[110:113], v[190:193], v[198:201], v[110:113]
	v_mfma_f32_16x16x32_bf16 v[102:105], v[182:185], v[206:209], v[102:105]
	v_mfma_f32_16x16x32_bf16 v[94:97], v[190:193], v[206:209], v[94:97]
	v_mfma_f32_16x16x32_bf16 v[86:89], v[182:185], v[214:217], v[86:89]
	v_mfma_f32_16x16x32_bf16 v[78:81], v[190:193], v[214:217], v[78:81]
	v_mfma_f32_16x16x32_bf16 v[70:73], v[182:185], v[222:225], v[70:73]
	v_mfma_f32_16x16x32_bf16 v[66:69], v[190:193], v[222:225], v[66:69]
	v_mfma_f32_16x16x32_bf16 v[118:121], v[186:189], v[202:205], v[118:121]
	v_mfma_f32_16x16x32_bf16 v[110:113], v[194:197], v[202:205], v[110:113]
	v_mfma_f32_16x16x32_bf16 v[102:105], v[186:189], v[210:213], v[102:105]
	v_mfma_f32_16x16x32_bf16 v[94:97], v[194:197], v[210:213], v[94:97]
	v_mfma_f32_16x16x32_bf16 v[86:89], v[186:189], v[218:221], v[86:89]
	v_mfma_f32_16x16x32_bf16 v[78:81], v[194:197], v[218:221], v[78:81]
	v_mfma_f32_16x16x32_bf16 v[70:73], v[186:189], v[226:229], v[70:73]
	v_mfma_f32_16x16x32_bf16 v[66:69], v[194:197], v[226:229], v[66:69]
	s_barrier
	s_add_u32 s100, s34, 0x80
	s_addc_u32 s101, s35, 0
	s_add_i32 s67, s70, s41
	s_mov_b32 m0, s67
	ds_read_b128 v[198:201], v173 offset:16384
	ds_read_b128 v[202:205], v173 offset:17408
	ds_read_b128 v[206:209], v173 offset:18432
	ds_read_b128 v[210:213], v173 offset:19456
	ds_read_b128 v[214:217], v173 offset:20480
	ds_read_b128 v[218:221], v173 offset:21504
	ds_read_b128 v[222:225], v173 offset:22528
	ds_read_b128 v[226:229], v173 offset:23552
	global_load_lds_dwordx4 v134, s[28:29]
	s_add_i32 m0, s67, 0x2000
	s_add_u32 s68, s28, 0x80000
	s_addc_u32 s69, s29, 0
	s_add_i32 s67, s71, s41
	global_load_lds_dwordx4 v130, s[28:29]
	s_mov_b32 m0, s67
	s_nop 0
	global_load_lds_dwordx4 v134, s[68:69]
	s_add_i32 m0, s67, 0x2000
	s_nop 0
	global_load_lds_dwordx4 v130, s[68:69]
	s_mov_b32 m0, s25
	s_nop 0
	global_load_lds_dwordx4 v136, s[34:35]
	s_mov_b32 m0, s52
	s_nop 0
	global_load_lds_dwordx4 v132, s[34:35]
	s_waitcnt vmcnt(8)
	s_waitcnt lgkmcnt(0)
	s_barrier
; #define PG8_STAGE(bufoff, gbase, voff) do { _Pragma("unroll") for (int _i = 0; _i < 2; ++_i) \
;         __builtin_amdgcn_global_load_lds((const unsigned*)((const char*)(gbase) + (voff)[_i]), (LAS unsigned*)(lds + (bufoff) + ldsw + _i * 8192), 16, 0, 0); } while (0)
; #define PG8_LDA(dst, b, h) do { _Pragma("unroll") for (int m = 0; m < 4; ++m) _Pragma("unroll") for (int k = 0; k < 2; ++k) dst[m][k] = *(const LAS bf16x8*)(lds + PG8_SA(b, h) + aoff + m * 2048 + k * 1024); } while (0)
; #define PG8_LDB(dst, b, h) do { _Pragma("unroll") for (int n = 0; n < 2; ++n) _Pragma("unroll") for (int k = 0; k < 2; ++k) dst[n][k] = *(const LAS bf16x8*)(lds + PG8_SB(b, h) + boff + n * 2048 + k * 1024); } while (0)
; #define PG8_MMA(ai, bj, At, Bt) do { __builtin_amdgcn_s_setprio(1); _Pragma("unroll") for (int m = 0; m < 4; ++m) _Pragma("unroll") for (int n = 0; n < 2; ++n) _Pragma("unroll") for (int k = 0; k < 2; ++k) \
;         acc[ai][bj][m][n] = __builtin_amdgcn_mfma_f32_16x16x32_bf16(Bt[n][k], At[m][k], acc[ai][bj][m][n], 0, 0, 0); __builtin_amdgcn_s_setprio(0); } while (0)
; #define PG8_WAIT_V(n) asm volatile("s_waitcnt vmcnt(" #n ")" ::: "memory")
; #define PG8_WAIT_L(n) asm volatile("s_waitcnt lgkmcnt(" #n ")" ::: "memory")
; #define PG8_BAR __builtin_amdgcn_s_barrier()
; #define PG8_SCHED __builtin_amdgcn_sched_barrier(0)
; template <class Epi, class Sched, int KC, bool ALIGN_EPI = false, bool SP2 = false, bool ATILED = false>
; __device__ __forceinline__ void gemm_phase(LAS unsigned char* lds, const Gemm g, const Sched& S, const Epi& E, int wave_s) {
;     ...
;             PG8_WAIT_V(8); PG8_WAIT_L(0); PG8_BAR; PG8_MMA(1, 0, At, B0); PG8_MMA(1, 1, At, B1); PG8_BAR; PG8_SCHED;
;             PG8_LDB(B0, 1, 0); PG8_LDB(B1, 1, 1); PG8_SCHED; PG8_LDA(At, 1, 0); PG8_STAGE(PG8_SA(0, 1), a2 + hstepA, voffA);
;             PG8_WAIT_V(8); PG8_WAIT_L(0); PG8_BAR; PG8_MMA(0, 0, At, B0); PG8_MMA(0, 1, At, B1); PG8_BAR; PG8_SCHED;
;             PG8_LDA(At, 1, 1); PG8_STAGE(PG8_SB(1, 0), b3, voffB); PG8_STAGE(PG8_SB(1, 1), b3 + hstepB, voffB); PG8_STAGE(PG8_SA(1, 0), a3, voffA);
	s_waitcnt lgkmcnt(0)
	v_mfma_f32_16x16x32_bf16 v[62:65], v[152:155], v[198:201], v[62:65]
	v_mfma_f32_16x16x32_bf16 v[58:61], v[174:177], v[198:201], v[58:61]
	v_mfma_f32_16x16x32_bf16 v[50:53], v[152:155], v[206:209], v[50:53]
	v_mfma_f32_16x16x32_bf16 v[42:45], v[174:177], v[206:209], v[42:45]
	v_mfma_f32_16x16x32_bf16 v[34:37], v[152:155], v[214:217], v[34:37]
	v_mfma_f32_16x16x32_bf16 v[26:29], v[174:177], v[214:217], v[26:29]
	v_mfma_f32_16x16x32_bf16 v[18:21], v[152:155], v[222:225], v[18:21]
	v_mfma_f32_16x16x32_bf16 v[10:13], v[174:177], v[222:225], v[10:13]
	v_mfma_f32_16x16x32_bf16 v[62:65], v[160:163], v[202:205], v[62:65]
	v_mfma_f32_16x16x32_bf16 v[58:61], v[178:181], v[202:205], v[58:61]
	v_mfma_f32_16x16x32_bf16 v[50:53], v[160:163], v[210:213], v[50:53]
	v_mfma_f32_16x16x32_bf16 v[42:45], v[178:181], v[210:213], v[42:45]
	v_mfma_f32_16x16x32_bf16 v[34:37], v[160:163], v[218:221], v[34:37]
	v_mfma_f32_16x16x32_bf16 v[26:29], v[178:181], v[218:221], v[26:29]
	v_mfma_f32_16x16x32_bf16 v[18:21], v[160:163], v[226:229], v[18:21]
	v_mfma_f32_16x16x32_bf16 v[10:13], v[178:181], v[226:229], v[10:13]
	v_mfma_f32_16x16x32_bf16 v[54:57], v[182:185], v[198:201], v[54:57]
	v_mfma_f32_16x16x32_bf16 v[46:49], v[190:193], v[198:201], v[46:49]
	v_mfma_f32_16x16x32_bf16 v[38:41], v[182:185], v[206:209], v[38:41]
	v_mfma_f32_16x16x32_bf16 v[30:33], v[190:193], v[206:209], v[30:33]
	v_mfma_f32_16x16x32_bf16 v[22:25], v[182:185], v[214:217], v[22:25]
	v_mfma_f32_16x16x32_bf16 v[14:17], v[190:193], v[214:217], v[14:17]
	v_mfma_f32_16x16x32_bf16 v[6:9], v[182:185], v[222:225], v[6:9]
	v_mfma_f32_16x16x32_bf16 v[2:5], v[190:193], v[222:225], v[2:5]
	v_mfma_f32_16x16x32_bf16 v[54:57], v[186:189], v[202:205], v[54:57]
	v_mfma_f32_16x16x32_bf16 v[46:49], v[194:197], v[202:205], v[46:49]
	v_mfma_f32_16x16x32_bf16 v[38:41], v[186:189], v[210:213], v[38:41]
	v_mfma_f32_16x16x32_bf16 v[30:33], v[194:197], v[210:213], v[30:33]
	v_mfma_f32_16x16x32_bf16 v[22:25], v[186:189], v[218:221], v[22:25]
	v_mfma_f32_16x16x32_bf16 v[14:17], v[194:197], v[218:221], v[14:17]
	v_mfma_f32_16x16x32_bf16 v[6:9], v[186:189], v[226:229], v[6:9]
	v_mfma_f32_16x16x32_bf16 v[2:5], v[194:197], v[226:229], v[2:5]
	s_barrier
	s_add_i32 s67, 0, 0x18000
	v_add_u32_e32 v139, s67, v165
	s_add_i32 s68, 0, 0x1c000
	ds_read_b128 v[152:155], v139
	ds_read_b128 v[160:163], v139 offset:1024
	ds_read_b128 v[174:177], v139 offset:2048
	ds_read_b128 v[178:181], v139 offset:3072
	v_add_u32_e32 v139, s68, v165
	ds_read_b128 v[182:185], v139
	ds_read_b128 v[186:189], v139 offset:1024
	ds_read_b128 v[190:193], v139 offset:2048
	ds_read_b128 v[194:197], v139 offset:3072
	s_add_u32 s34, s34, 0x10000
	s_addc_u32 s35, s35, 0
	s_mov_b32 m0, s53
	ds_read_b128 v[198:201], v173 offset:32768
	ds_read_b128 v[202:205], v173 offset:33792
	ds_read_b128 v[206:209], v173 offset:34816
	ds_read_b128 v[210:213], v173 offset:35840
	ds_read_b128 v[214:217], v173 offset:36864
	ds_read_b128 v[218:221], v173 offset:37888
	ds_read_b128 v[222:225], v173 offset:38912
	ds_read_b128 v[226:229], v173 offset:39936
	global_load_lds_dwordx4 v136, s[34:35]
	s_mov_b32 m0, s54
	s_nop 0
	global_load_lds_dwordx4 v132, s[34:35]
	s_waitcnt vmcnt(8)
	s_waitcnt lgkmcnt(0)
	s_barrier
	s_waitcnt lgkmcnt(0)
	v_mfma_f32_16x16x32_bf16 v[126:129], v[152:155], v[198:201], v[126:129]
	v_mfma_f32_16x16x32_bf16 v[122:125], v[174:177], v[198:201], v[122:125]
	v_mfma_f32_16x16x32_bf16 v[114:117], v[152:155], v[206:209], v[114:117]
	v_mfma_f32_16x16x32_bf16 v[106:109], v[174:177], v[206:209], v[106:109]
	v_mfma_f32_16x16x32_bf16 v[98:101], v[152:155], v[214:217], v[98:101]
	v_mfma_f32_16x16x32_bf16 v[90:93], v[174:177], v[214:217], v[90:93]
	v_mfma_f32_16x16x32_bf16 v[82:85], v[152:155], v[222:225], v[82:85]
	v_mfma_f32_16x16x32_bf16 v[74:77], v[174:177], v[222:225], v[74:77]
	v_mfma_f32_16x16x32_bf16 v[126:129], v[160:163], v[202:205], v[126:129]
	v_mfma_f32_16x16x32_bf16 v[122:125], v[178:181], v[202:205], v[122:125]
	v_mfma_f32_16x16x32_bf16 v[114:117], v[160:163], v[210:213], v[114:117]
	v_mfma_f32_16x16x32_bf16 v[106:109], v[178:181], v[210:213], v[106:109]
	v_mfma_f32_16x16x32_bf16 v[98:101], v[160:163], v[218:221], v[98:101]
	v_mfma_f32_16x16x32_bf16 v[90:93], v[178:181], v[218:221], v[90:93]
	v_mfma_f32_16x16x32_bf16 v[82:85], v[160:163], v[226:229], v[82:85]
	v_mfma_f32_16x16x32_bf16 v[74:77], v[178:181], v[226:229], v[74:77]
	v_mfma_f32_16x16x32_bf16 v[118:121], v[182:185], v[198:201], v[118:121]
	v_mfma_f32_16x16x32_bf16 v[110:113], v[190:193], v[198:201], v[110:113]
	v_mfma_f32_16x16x32_bf16 v[102:105], v[182:185], v[206:209], v[102:105]
	v_mfma_f32_16x16x32_bf16 v[94:97], v[190:193], v[206:209], v[94:97]
	v_mfma_f32_16x16x32_bf16 v[86:89], v[182:185], v[214:217], v[86:89]
	v_mfma_f32_16x16x32_bf16 v[78:81], v[190:193], v[214:217], v[78:81]
	v_mfma_f32_16x16x32_bf16 v[70:73], v[182:185], v[222:225], v[70:73]
	v_mfma_f32_16x16x32_bf16 v[66:69], v[190:193], v[222:225], v[66:69]
	v_mfma_f32_16x16x32_bf16 v[118:121], v[186:189], v[202:205], v[118:121]
	v_mfma_f32_16x16x32_bf16 v[110:113], v[194:197], v[202:205], v[110:113]
	v_mfma_f32_16x16x32_bf16 v[102:105], v[186:189], v[210:213], v[102:105]
	v_mfma_f32_16x16x32_bf16 v[94:97], v[194:197], v[210:213], v[94:97]
	v_mfma_f32_16x16x32_bf16 v[86:89], v[186:189], v[218:221], v[86:89]
	v_mfma_f32_16x16x32_bf16 v[78:81], v[194:197], v[218:221], v[78:81]
	v_mfma_f32_16x16x32_bf16 v[70:73], v[186:189], v[226:229], v[70:73]
	v_mfma_f32_16x16x32_bf16 v[66:69], v[194:197], v[226:229], v[66:69]
	s_barrier
; #define PG8_STAGE(bufoff, gbase, voff) do { _Pragma("unroll") for (int _i = 0; _i < 2; ++_i) \
;         __builtin_amdgcn_global_load_lds((const unsigned*)((const char*)(gbase) + (voff)[_i]), (LAS unsigned*)(lds + (bufoff) + ldsw + _i * 8192), 16, 0, 0); } while (0)
; #define PG8_LDA(dst, b, h) do { _Pragma("unroll") for (int m = 0; m < 4; ++m) _Pragma("unroll") for (int k = 0; k < 2; ++k) dst[m][k] = *(const LAS bf16x8*)(lds + PG8_SA(b, h) + aoff + m * 2048 + k * 1024); } while (0)
; #define PG8_MMA(ai, bj, At, Bt) do { __builtin_amdgcn_s_setprio(1); _Pragma("unroll") for (int m = 0; m < 4; ++m) _Pragma("unroll") for (int n = 0; n < 2; ++n) _Pragma("unroll") for (int k = 0; k < 2; ++k) \
;         acc[ai][bj][m][n] = __builtin_amdgcn_mfma_f32_16x16x32_bf16(Bt[n][k], At[m][k], acc[ai][bj][m][n], 0, 0, 0); __builtin_amdgcn_s_setprio(0); } while (0)
; #define PG8_WAIT_V(n) asm volatile("s_waitcnt vmcnt(" #n ")" ::: "memory")
; #define PG8_WAIT_L(n) asm volatile("s_waitcnt lgkmcnt(" #n ")" ::: "memory")
; #define PG8_BAR __builtin_amdgcn_s_barrier()
; #define PG8_SCHED __builtin_amdgcn_sched_barrier(0)
; template <class Epi, class Sched, int KC, bool ALIGN_EPI = false, bool SP2 = false, bool ATILED = false>
; __device__ __forceinline__ void gemm_phase(LAS unsigned char* lds, const Gemm g, const Sched& S, const Epi& E, int wave_s) {
;     ...
;             PG8_LDA(At, 1, 1); PG8_STAGE(PG8_SB(1, 0), b3, voffB); PG8_STAGE(PG8_SB(1, 1), b3 + hstepB, voffB); PG8_STAGE(PG8_SA(1, 0), a3, voffA);
;             PG8_WAIT_V(8); PG8_WAIT_L(0); PG8_BAR; PG8_MMA(1, 0, At, B0); PG8_MMA(1, 1, At, B1); PG8_BAR; PG8_SCHED;
;     ...
;         if constexpr (ALIGN_EPI) { if (wr == 0) PG8_BAR; }
	s_add_u32 s98, s28, 0x80
	s_addc_u32 s99, s29, 0
	s_add_i32 s34, s67, s41
	s_mov_b32 m0, s34
	ds_read_b128 v[198:201], v173 offset:49152
	ds_read_b128 v[202:205], v173 offset:50176
	ds_read_b128 v[206:209], v173 offset:51200
	ds_read_b128 v[210:213], v173 offset:52224
	ds_read_b128 v[214:217], v173 offset:53248
	ds_read_b128 v[218:221], v173 offset:54272
	ds_read_b128 v[222:225], v173 offset:55296
	ds_read_b128 v[226:229], v173 offset:56320
	global_load_lds_dwordx4 v134, s[98:99]
	s_add_i32 m0, s34, 0x2000
	s_add_u32 s28, s28, 0x80080
	s_addc_u32 s29, s29, 0
	s_add_i32 s34, s68, s41
	global_load_lds_dwordx4 v130, s[98:99]
	s_mov_b32 m0, s34
	s_nop 0
	global_load_lds_dwordx4 v134, s[28:29]
	s_add_i32 m0, s34, 0x2000
	s_nop 0
	global_load_lds_dwordx4 v130, s[28:29]
	s_mov_b32 m0, s55
	s_nop 0
	global_load_lds_dwordx4 v136, s[100:101]
	s_mov_b32 m0, s56
	s_nop 0
	global_load_lds_dwordx4 v132, s[100:101]
	s_waitcnt vmcnt(8)
	s_waitcnt lgkmcnt(0)
	s_barrier
	s_waitcnt lgkmcnt(0)
	v_mfma_f32_16x16x32_bf16 v[62:65], v[152:155], v[198:201], v[62:65]
	v_mfma_f32_16x16x32_bf16 v[58:61], v[174:177], v[198:201], v[58:61]
	v_mfma_f32_16x16x32_bf16 v[50:53], v[152:155], v[206:209], v[50:53]
	v_mfma_f32_16x16x32_bf16 v[42:45], v[174:177], v[206:209], v[42:45]
	v_mfma_f32_16x16x32_bf16 v[34:37], v[152:155], v[214:217], v[34:37]
	v_mfma_f32_16x16x32_bf16 v[26:29], v[174:177], v[214:217], v[26:29]
	v_mfma_f32_16x16x32_bf16 v[18:21], v[152:155], v[222:225], v[18:21]
	v_mfma_f32_16x16x32_bf16 v[10:13], v[174:177], v[222:225], v[10:13]
	v_mfma_f32_16x16x32_bf16 v[62:65], v[160:163], v[202:205], v[62:65]
	v_mfma_f32_16x16x32_bf16 v[58:61], v[178:181], v[202:205], v[58:61]
	v_mfma_f32_16x16x32_bf16 v[50:53], v[160:163], v[210:213], v[50:53]
	v_mfma_f32_16x16x32_bf16 v[42:45], v[178:181], v[210:213], v[42:45]
	v_mfma_f32_16x16x32_bf16 v[34:37], v[160:163], v[218:221], v[34:37]
	v_mfma_f32_16x16x32_bf16 v[26:29], v[178:181], v[218:221], v[26:29]
	v_mfma_f32_16x16x32_bf16 v[18:21], v[160:163], v[226:229], v[18:21]
	v_mfma_f32_16x16x32_bf16 v[10:13], v[178:181], v[226:229], v[10:13]
	v_mfma_f32_16x16x32_bf16 v[54:57], v[182:185], v[198:201], v[54:57]
	v_mfma_f32_16x16x32_bf16 v[46:49], v[190:193], v[198:201], v[46:49]
	v_mfma_f32_16x16x32_bf16 v[38:41], v[182:185], v[206:209], v[38:41]
	v_mfma_f32_16x16x32_bf16 v[30:33], v[190:193], v[206:209], v[30:33]
	v_mfma_f32_16x16x32_bf16 v[22:25], v[182:185], v[214:217], v[22:25]
	v_mfma_f32_16x16x32_bf16 v[14:17], v[190:193], v[214:217], v[14:17]
	v_mfma_f32_16x16x32_bf16 v[6:9], v[182:185], v[222:225], v[6:9]
	v_mfma_f32_16x16x32_bf16 v[2:5], v[190:193], v[222:225], v[2:5]
	v_mfma_f32_16x16x32_bf16 v[54:57], v[186:189], v[202:205], v[54:57]
	v_mfma_f32_16x16x32_bf16 v[46:49], v[194:197], v[202:205], v[46:49]
	v_mfma_f32_16x16x32_bf16 v[38:41], v[186:189], v[210:213], v[38:41]
	v_mfma_f32_16x16x32_bf16 v[30:33], v[194:197], v[210:213], v[30:33]
	v_mfma_f32_16x16x32_bf16 v[22:25], v[186:189], v[218:221], v[22:25]
	v_mfma_f32_16x16x32_bf16 v[14:17], v[194:197], v[218:221], v[14:17]
	v_mfma_f32_16x16x32_bf16 v[6:9], v[186:189], v[226:229], v[6:9]
	v_mfma_f32_16x16x32_bf16 v[2:5], v[194:197], v[226:229], v[2:5]
	s_barrier
	s_add_i32 s65, s65, 2
	s_add_i32 s66, s66, 0x400000
	s_cmp_gt_u32 s65, 29
	s_mov_b64 s[28:29], s[30:31]
	s_cbranch_scc0 .LBB0_430
	s_and_b64 vcc, exec, s[14:15]
	s_cbranch_vccz .LBB0_433
	s_barrier

; #define PG8_STAGE(bufoff, gbase, voff) do { _Pragma("unroll") for (int _i = 0; _i < 2; ++_i) \
;         __builtin_amdgcn_global_load_lds((const unsigned*)((const char*)(gbase) + (voff)[_i]), (LAS unsigned*)(lds + (bufoff) + ldsw + _i * 8192), 16, 0, 0); } while (0)
; #define PG8_LDA(dst, b, h) do { _Pragma("unroll") for (int m = 0; m < 4; ++m) _Pragma("unroll") for (int k = 0; k < 2; ++k) dst[m][k] = *(const LAS bf16x8*)(lds + PG8_SA(b, h) + aoff + m * 2048 + k * 1024); } while (0)
; #define PG8_LDB(dst, b, h) do { _Pragma("unroll") for (int n = 0; n < 2; ++n) _Pragma("unroll") for (int k = 0; k < 2; ++k) dst[n][k] = *(const LAS bf16x8*)(lds + PG8_SB(b, h) + boff + n * 2048 + k * 1024); } while (0)
; #define PG8_MMA(ai, bj, At, Bt) do { __builtin_amdgcn_s_setprio(1); _Pragma("unroll") for (int m = 0; m < 4; ++m) _Pragma("unroll") for (int n = 0; n < 2; ++n) _Pragma("unroll") for (int k = 0; k < 2; ++k) \
;         acc[ai][bj][m][n] = __builtin_amdgcn_mfma_f32_16x16x32_bf16(Bt[n][k], At[m][k], acc[ai][bj][m][n], 0, 0, 0); __builtin_amdgcn_s_setprio(0); } while (0)
; #define PG8_WAIT_V(n) asm volatile("s_waitcnt vmcnt(" #n ")" ::: "memory")
; #define PG8_BAR __builtin_amdgcn_s_barrier()
; template <class Epi, class Sched, int KC, bool ALIGN_EPI = false, bool SP2 = false, bool ATILED = false>
; __device__ __forceinline__ void gemm_phase(LAS unsigned char* lds, const Gemm g, const Sched& S, const Epi& E, int wave_s) {
;     ...
;         for (int t = 0; t < nt; t += 2) {
;             const bool last = (t == nt - 2);
;             const char* a1 = cA + PG8_AOFF(t + 1);
;             const char* a2 = last ? nA : cA + PG8_AOFF(t + 2); const char* b2 = last ? nB : cB + (size_t)(t + 2) * kstep;
;             const char* a3 = a2 + kstep; const char* b3 = b2 + kstep;
;             if (last && has_next) S.a_ready(nxt);
;             if constexpr (SP2) {
;             PG8_LDB(B0, 0, 0); PG8_LDB(B1, 0, 1); PG8_SCHED; PG8_LDA(At, 0, 0); PG8_STAGE(PG8_SA(1, 1), a1 + hstepA, voffA);
;             PG8_WAIT_V(8); PG8_WAIT_L(0); PG8_BAR; PG8_MMA(0, 0, At, B0); PG8_MMA(0, 1, At, B1); PG8_BAR; PG8_SCHED;
;             PG8_LDA(At, 0, 1); PG8_STAGE(PG8_SB(0, 0), b2, voffB); PG8_STAGE(PG8_SB(0, 1), b2 + hstepB, voffB); PG8_STAGE(PG8_SA(0, 0), a2, voffA);
;             PG8_WAIT_V(8); PG8_WAIT_L(0); PG8_BAR; PG8_MMA(1, 0, At, B0); PG8_MMA(1, 1, At, B1); PG8_BAR; PG8_SCHED;
.LBB0_1021:
	s_add_u32 s20, s18, 0xfff80080
	s_addc_u32 s21, s19, -1
	s_add_i32 s49, 0, 0x10000
	s_cmp_eq_u32 s48, 28
	s_cselect_b32 s23, s9, s21
	s_cselect_b32 s22, s15, s20
	s_cselect_b32 s21, s3, s47
	s_cselect_b32 s20, s17, s46
	s_add_i32 s52, 0, 0x14000
	v_add_u32_e32 v142, s49, v229
	v_add_u32_e32 v158, s52, v229
	ds_read_b128 v[130:133], v142
	ds_read_b128 v[134:137], v142 offset:1024
	ds_read_b128 v[138:141], v142 offset:2048
	ds_read_b128 v[142:145], v142 offset:3072
	ds_read_b128 v[146:149], v158
	ds_read_b128 v[150:153], v158 offset:1024
	ds_read_b128 v[154:157], v158 offset:2048
	ds_read_b128 v[158:161], v158 offset:3072
	s_add_i32 m0, s34, 0xc000
	ds_read_b128 v[162:165], v230
	ds_read_b128 v[166:169], v230 offset:1024
	ds_read_b128 v[170:173], v230 offset:2048
	ds_read_b128 v[174:177], v230 offset:3072
	ds_read_b128 v[178:181], v230 offset:4096
	ds_read_b128 v[182:185], v230 offset:5120
	ds_read_b128 v[186:189], v230 offset:6144
	ds_read_b128 v[190:193], v230 offset:7168
	global_load_lds_dwordx4 v208, s[18:19]
	s_add_i32 m0, s34, 0xe000
	s_nop 0
	global_load_lds_dwordx4 v206, s[18:19]
	s_waitcnt vmcnt(8)
	s_waitcnt lgkmcnt(0)
	s_barrier
	s_waitcnt lgkmcnt(0)
	v_mfma_f32_16x16x32_bf16 v[126:129], v[130:133], v[162:165], v[126:129]
	v_mfma_f32_16x16x32_bf16 v[122:125], v[138:141], v[162:165], v[122:125]
	v_mfma_f32_16x16x32_bf16 v[110:113], v[130:133], v[170:173], v[110:113]
	v_mfma_f32_16x16x32_bf16 v[106:109], v[138:141], v[170:173], v[106:109]
	v_mfma_f32_16x16x32_bf16 v[94:97], v[130:133], v[178:181], v[94:97]
	v_mfma_f32_16x16x32_bf16 v[90:93], v[138:141], v[178:181], v[90:93]
	v_mfma_f32_16x16x32_bf16 v[78:81], v[130:133], v[186:189], v[78:81]
	v_mfma_f32_16x16x32_bf16 v[74:77], v[138:141], v[186:189], v[74:77]
	v_mfma_f32_16x16x32_bf16 v[126:129], v[134:137], v[166:169], v[126:129]
	v_mfma_f32_16x16x32_bf16 v[122:125], v[142:145], v[166:169], v[122:125]
	v_mfma_f32_16x16x32_bf16 v[110:113], v[134:137], v[174:177], v[110:113]
	v_mfma_f32_16x16x32_bf16 v[106:109], v[142:145], v[174:177], v[106:109]
	v_mfma_f32_16x16x32_bf16 v[94:97], v[134:137], v[182:185], v[94:97]
	v_mfma_f32_16x16x32_bf16 v[90:93], v[142:145], v[182:185], v[90:93]
	v_mfma_f32_16x16x32_bf16 v[78:81], v[134:137], v[190:193], v[78:81]
	v_mfma_f32_16x16x32_bf16 v[74:77], v[142:145], v[190:193], v[74:77]
	v_mfma_f32_16x16x32_bf16 v[118:121], v[146:149], v[162:165], v[118:121]
	v_mfma_f32_16x16x32_bf16 v[114:117], v[154:157], v[162:165], v[114:117]
	v_mfma_f32_16x16x32_bf16 v[102:105], v[146:149], v[170:173], v[102:105]
	v_mfma_f32_16x16x32_bf16 v[98:101], v[154:157], v[170:173], v[98:101]
	v_mfma_f32_16x16x32_bf16 v[86:89], v[146:149], v[178:181], v[86:89]
	v_mfma_f32_16x16x32_bf16 v[82:85], v[154:157], v[178:181], v[82:85]
	v_mfma_f32_16x16x32_bf16 v[70:73], v[146:149], v[186:189], v[70:73]
	v_mfma_f32_16x16x32_bf16 v[66:69], v[154:157], v[186:189], v[66:69]
	v_mfma_f32_16x16x32_bf16 v[118:121], v[150:153], v[166:169], v[118:121]
	v_mfma_f32_16x16x32_bf16 v[114:117], v[158:161], v[166:169], v[114:117]
	v_mfma_f32_16x16x32_bf16 v[102:105], v[150:153], v[174:177], v[102:105]
	v_mfma_f32_16x16x32_bf16 v[98:101], v[158:161], v[174:177], v[98:101]
	v_mfma_f32_16x16x32_bf16 v[86:89], v[150:153], v[182:185], v[86:89]
	v_mfma_f32_16x16x32_bf16 v[82:85], v[158:161], v[182:185], v[82:85]
	v_mfma_f32_16x16x32_bf16 v[70:73], v[150:153], v[190:193], v[70:73]
	v_mfma_f32_16x16x32_bf16 v[66:69], v[158:161], v[190:193], v[66:69]
	s_barrier
	s_add_u32 s100, s22, 0x80
	s_addc_u32 s101, s23, 0
	s_add_i32 s49, s49, s31
	s_mov_b32 m0, s49
	ds_read_b128 v[162:165], v230 offset:16384
	ds_read_b128 v[166:169], v230 offset:17408
	ds_read_b128 v[170:173], v230 offset:18432
	ds_read_b128 v[174:177], v230 offset:19456
	ds_read_b128 v[178:181], v230 offset:20480
	ds_read_b128 v[182:185], v230 offset:21504
	ds_read_b128 v[186:189], v230 offset:22528
	ds_read_b128 v[190:193], v230 offset:23552
	global_load_lds_dwordx4 v0, s[20:21]
	s_add_i32 m0, s49, 0x2000
	s_add_u32 s50, s20, 0x20000
	s_addc_u32 s51, s21, 0
	s_add_i32 s49, s52, s31
	global_load_lds_dwordx4 v202, s[20:21]
	s_mov_b32 m0, s49
	s_nop 0
	global_load_lds_dwordx4 v0, s[50:51]
	s_add_i32 m0, s49, 0x2000
	s_nop 0
	global_load_lds_dwordx4 v202, s[50:51]
	s_mov_b32 m0, s34
	s_nop 0
	global_load_lds_dwordx4 v198, s[22:23]
	s_mov_b32 m0, s35
	s_nop 0
	global_load_lds_dwordx4 v200, s[22:23]
	s_waitcnt vmcnt(8)
	s_waitcnt lgkmcnt(0)
	s_barrier
	s_waitcnt lgkmcnt(0)
	v_mfma_f32_16x16x32_bf16 v[62:65], v[130:133], v[162:165], v[62:65]
	v_mfma_f32_16x16x32_bf16 v[58:61], v[138:141], v[162:165], v[58:61]
	v_mfma_f32_16x16x32_bf16 v[46:49], v[130:133], v[170:173], v[46:49]
	v_mfma_f32_16x16x32_bf16 v[42:45], v[138:141], v[170:173], v[42:45]
	v_mfma_f32_16x16x32_bf16 v[30:33], v[130:133], v[178:181], v[30:33]
	v_mfma_f32_16x16x32_bf16 v[26:29], v[138:141], v[178:181], v[26:29]
	v_mfma_f32_16x16x32_bf16 v[14:17], v[130:133], v[186:189], v[14:17]
	v_mfma_f32_16x16x32_bf16 v[10:13], v[138:141], v[186:189], v[10:13]
	v_mfma_f32_16x16x32_bf16 v[62:65], v[134:137], v[166:169], v[62:65]
	v_mfma_f32_16x16x32_bf16 v[58:61], v[142:145], v[166:169], v[58:61]
	v_mfma_f32_16x16x32_bf16 v[46:49], v[134:137], v[174:177], v[46:49]
	v_mfma_f32_16x16x32_bf16 v[42:45], v[142:145], v[174:177], v[42:45]
	v_mfma_f32_16x16x32_bf16 v[30:33], v[134:137], v[182:185], v[30:33]
	v_mfma_f32_16x16x32_bf16 v[26:29], v[142:145], v[182:185], v[26:29]
	v_mfma_f32_16x16x32_bf16 v[14:17], v[134:137], v[190:193], v[14:17]
	v_mfma_f32_16x16x32_bf16 v[10:13], v[142:145], v[190:193], v[10:13]
	v_mfma_f32_16x16x32_bf16 v[54:57], v[146:149], v[162:165], v[54:57]
	v_mfma_f32_16x16x32_bf16 v[50:53], v[154:157], v[162:165], v[50:53]
	v_mfma_f32_16x16x32_bf16 v[38:41], v[146:149], v[170:173], v[38:41]
	v_mfma_f32_16x16x32_bf16 v[34:37], v[154:157], v[170:173], v[34:37]
	v_mfma_f32_16x16x32_bf16 v[22:25], v[146:149], v[178:181], v[22:25]
	v_mfma_f32_16x16x32_bf16 v[18:21], v[154:157], v[178:181], v[18:21]
	v_mfma_f32_16x16x32_bf16 v[6:9], v[146:149], v[186:189], v[6:9]
	v_mfma_f32_16x16x32_bf16 v[2:5], v[154:157], v[186:189], v[2:5]
	v_mfma_f32_16x16x32_bf16 v[54:57], v[150:153], v[166:169], v[54:57]
	v_mfma_f32_16x16x32_bf16 v[50:53], v[158:161], v[166:169], v[50:53]
	v_mfma_f32_16x16x32_bf16 v[38:41], v[150:153], v[174:177], v[38:41]
	v_mfma_f32_16x16x32_bf16 v[34:37], v[158:161], v[174:177], v[34:37]
	v_mfma_f32_16x16x32_bf16 v[22:25], v[150:153], v[182:185], v[22:25]
	v_mfma_f32_16x16x32_bf16 v[18:21], v[158:161], v[182:185], v[18:21]
	v_mfma_f32_16x16x32_bf16 v[6:9], v[150:153], v[190:193], v[6:9]
	v_mfma_f32_16x16x32_bf16 v[2:5], v[158:161], v[190:193], v[2:5]
	s_barrier
; #define PG8_STAGE(bufoff, gbase, voff) do { _Pragma("unroll") for (int _i = 0; _i < 2; ++_i) \
;         __builtin_amdgcn_global_load_lds((const unsigned*)((const char*)(gbase) + (voff)[_i]), (LAS unsigned*)(lds + (bufoff) + ldsw + _i * 8192), 16, 0, 0); } while (0)
; #define PG8_LDA(dst, b, h) do { _Pragma("unroll") for (int m = 0; m < 4; ++m) _Pragma("unroll") for (int k = 0; k < 2; ++k) dst[m][k] = *(const LAS bf16x8*)(lds + PG8_SA(b, h) + aoff + m * 2048 + k * 1024); } while (0)
; #define PG8_LDB(dst, b, h) do { _Pragma("unroll") for (int n = 0; n < 2; ++n) _Pragma("unroll") for (int k = 0; k < 2; ++k) dst[n][k] = *(const LAS bf16x8*)(lds + PG8_SB(b, h) + boff + n * 2048 + k * 1024); } while (0)
; #define PG8_MMA(ai, bj, At, Bt) do { __builtin_amdgcn_s_setprio(1); _Pragma("unroll") for (int m = 0; m < 4; ++m) _Pragma("unroll") for (int n = 0; n < 2; ++n) _Pragma("unroll") for (int k = 0; k < 2; ++k) \
;         acc[ai][bj][m][n] = __builtin_amdgcn_mfma_f32_16x16x32_bf16(Bt[n][k], At[m][k], acc[ai][bj][m][n], 0, 0, 0); __builtin_amdgcn_s_setprio(0); } while (0)
; #define PG8_WAIT_V(n) asm volatile("s_waitcnt vmcnt(" #n ")" ::: "memory")
; #define PG8_WAIT_L(n) asm volatile("s_waitcnt lgkmcnt(" #n ")" ::: "memory")
; #define PG8_BAR __builtin_amdgcn_s_barrier()
; #define PG8_SCHED __builtin_amdgcn_sched_barrier(0)
; template <class Epi, class Sched, int KC, bool ALIGN_EPI = false, bool SP2 = false, bool ATILED = false>
; __device__ __forceinline__ void gemm_phase(LAS unsigned char* lds, const Gemm g, const Sched& S, const Epi& E, int wave_s) {
;     ...
;             PG8_LDB(B0, 1, 0); PG8_LDB(B1, 1, 1); PG8_SCHED; PG8_LDA(At, 1, 0); PG8_STAGE(PG8_SA(0, 1), a2 + hstepA, voffA);
;             PG8_WAIT_V(8); PG8_WAIT_L(0); PG8_BAR; PG8_MMA(0, 0, At, B0); PG8_MMA(0, 1, At, B1); PG8_BAR; PG8_SCHED;
;             PG8_LDA(At, 1, 1); PG8_STAGE(PG8_SB(1, 0), b3, voffB); PG8_STAGE(PG8_SB(1, 1), b3 + hstepB, voffB); PG8_STAGE(PG8_SA(1, 0), a3, voffA);
;             PG8_WAIT_V(8); PG8_WAIT_L(0); PG8_BAR; PG8_MMA(1, 0, At, B0); PG8_MMA(1, 1, At, B1); PG8_BAR; PG8_SCHED;
	s_add_i32 s49, 0, 0x18000
	s_add_i32 s50, 0, 0x1c000
	v_add_u32_e32 v142, s49, v229
	v_add_u32_e32 v158, s50, v229
	ds_read_b128 v[130:133], v142
	ds_read_b128 v[134:137], v142 offset:1024
	ds_read_b128 v[138:141], v142 offset:2048
	ds_read_b128 v[142:145], v142 offset:3072
	ds_read_b128 v[146:149], v158
	ds_read_b128 v[150:153], v158 offset:1024
	ds_read_b128 v[154:157], v158 offset:2048
	ds_read_b128 v[158:161], v158 offset:3072
	s_add_u32 s22, s22, 0x80000
	s_addc_u32 s23, s23, 0
	s_mov_b32 m0, s36
	ds_read_b128 v[162:165], v230 offset:32768
	ds_read_b128 v[166:169], v230 offset:33792
	ds_read_b128 v[170:173], v230 offset:34816
	ds_read_b128 v[174:177], v230 offset:35840
	ds_read_b128 v[178:181], v230 offset:36864
	ds_read_b128 v[182:185], v230 offset:37888
	ds_read_b128 v[186:189], v230 offset:38912
	ds_read_b128 v[190:193], v230 offset:39936
	global_load_lds_dwordx4 v198, s[22:23]
	s_mov_b32 m0, s37
	s_nop 0
	global_load_lds_dwordx4 v200, s[22:23]
	s_waitcnt vmcnt(8)
	s_waitcnt lgkmcnt(0)
	s_barrier
	s_waitcnt lgkmcnt(0)
	v_mfma_f32_16x16x32_bf16 v[126:129], v[130:133], v[162:165], v[126:129]
	v_mfma_f32_16x16x32_bf16 v[122:125], v[138:141], v[162:165], v[122:125]
	v_mfma_f32_16x16x32_bf16 v[110:113], v[130:133], v[170:173], v[110:113]
	v_mfma_f32_16x16x32_bf16 v[106:109], v[138:141], v[170:173], v[106:109]
	v_mfma_f32_16x16x32_bf16 v[94:97], v[130:133], v[178:181], v[94:97]
	v_mfma_f32_16x16x32_bf16 v[90:93], v[138:141], v[178:181], v[90:93]
	v_mfma_f32_16x16x32_bf16 v[78:81], v[130:133], v[186:189], v[78:81]
	v_mfma_f32_16x16x32_bf16 v[74:77], v[138:141], v[186:189], v[74:77]
	v_mfma_f32_16x16x32_bf16 v[126:129], v[134:137], v[166:169], v[126:129]
	v_mfma_f32_16x16x32_bf16 v[122:125], v[142:145], v[166:169], v[122:125]
	v_mfma_f32_16x16x32_bf16 v[110:113], v[134:137], v[174:177], v[110:113]
	v_mfma_f32_16x16x32_bf16 v[106:109], v[142:145], v[174:177], v[106:109]
	v_mfma_f32_16x16x32_bf16 v[94:97], v[134:137], v[182:185], v[94:97]
	v_mfma_f32_16x16x32_bf16 v[90:93], v[142:145], v[182:185], v[90:93]
	v_mfma_f32_16x16x32_bf16 v[78:81], v[134:137], v[190:193], v[78:81]
	v_mfma_f32_16x16x32_bf16 v[74:77], v[142:145], v[190:193], v[74:77]
	v_mfma_f32_16x16x32_bf16 v[118:121], v[146:149], v[162:165], v[118:121]
	v_mfma_f32_16x16x32_bf16 v[114:117], v[154:157], v[162:165], v[114:117]
	v_mfma_f32_16x16x32_bf16 v[102:105], v[146:149], v[170:173], v[102:105]
	v_mfma_f32_16x16x32_bf16 v[98:101], v[154:157], v[170:173], v[98:101]
	v_mfma_f32_16x16x32_bf16 v[86:89], v[146:149], v[178:181], v[86:89]
	v_mfma_f32_16x16x32_bf16 v[82:85], v[154:157], v[178:181], v[82:85]
	v_mfma_f32_16x16x32_bf16 v[70:73], v[146:149], v[186:189], v[70:73]
	v_mfma_f32_16x16x32_bf16 v[66:69], v[154:157], v[186:189], v[66:69]
	v_mfma_f32_16x16x32_bf16 v[118:121], v[150:153], v[166:169], v[118:121]
	v_mfma_f32_16x16x32_bf16 v[114:117], v[158:161], v[166:169], v[114:117]
	v_mfma_f32_16x16x32_bf16 v[102:105], v[150:153], v[174:177], v[102:105]
	v_mfma_f32_16x16x32_bf16 v[98:101], v[158:161], v[174:177], v[98:101]
	v_mfma_f32_16x16x32_bf16 v[86:89], v[150:153], v[182:185], v[86:89]
	v_mfma_f32_16x16x32_bf16 v[82:85], v[158:161], v[182:185], v[82:85]
	v_mfma_f32_16x16x32_bf16 v[70:73], v[150:153], v[190:193], v[70:73]
	v_mfma_f32_16x16x32_bf16 v[66:69], v[158:161], v[190:193], v[66:69]
	s_barrier
	s_add_u32 s98, s20, 0x80
	s_addc_u32 s99, s21, 0
	s_add_i32 s22, s49, s31
	s_mov_b32 m0, s22
	ds_read_b128 v[162:165], v230 offset:49152
	ds_read_b128 v[166:169], v230 offset:50176
	ds_read_b128 v[170:173], v230 offset:51200
	ds_read_b128 v[174:177], v230 offset:52224
	ds_read_b128 v[178:181], v230 offset:53248
	ds_read_b128 v[182:185], v230 offset:54272
	ds_read_b128 v[186:189], v230 offset:55296
	ds_read_b128 v[190:193], v230 offset:56320
	global_load_lds_dwordx4 v0, s[98:99]
	s_add_i32 m0, s22, 0x2000
	s_add_u32 s20, s20, 0x20080
	s_addc_u32 s21, s21, 0
	s_add_i32 s22, s50, s31
	global_load_lds_dwordx4 v202, s[98:99]
	s_mov_b32 m0, s22
	s_nop 0
	global_load_lds_dwordx4 v0, s[20:21]
	s_add_i32 m0, s22, 0x2000
	s_nop 0
	global_load_lds_dwordx4 v202, s[20:21]
	s_mov_b32 m0, s41
	s_nop 0
	global_load_lds_dwordx4 v198, s[100:101]
	s_mov_b32 m0, s42
	s_nop 0
	global_load_lds_dwordx4 v200, s[100:101]
	s_waitcnt vmcnt(8)
	s_waitcnt lgkmcnt(0)
	s_barrier
	s_waitcnt lgkmcnt(0)
	v_mfma_f32_16x16x32_bf16 v[62:65], v[130:133], v[162:165], v[62:65]
	v_mfma_f32_16x16x32_bf16 v[58:61], v[138:141], v[162:165], v[58:61]
	v_mfma_f32_16x16x32_bf16 v[46:49], v[130:133], v[170:173], v[46:49]
	v_mfma_f32_16x16x32_bf16 v[42:45], v[138:141], v[170:173], v[42:45]
	v_mfma_f32_16x16x32_bf16 v[30:33], v[130:133], v[178:181], v[30:33]
	v_mfma_f32_16x16x32_bf16 v[26:29], v[138:141], v[178:181], v[26:29]
	v_mfma_f32_16x16x32_bf16 v[14:17], v[130:133], v[186:189], v[14:17]
	v_mfma_f32_16x16x32_bf16 v[10:13], v[138:141], v[186:189], v[10:13]
	v_mfma_f32_16x16x32_bf16 v[62:65], v[134:137], v[166:169], v[62:65]
	v_mfma_f32_16x16x32_bf16 v[58:61], v[142:145], v[166:169], v[58:61]
	v_mfma_f32_16x16x32_bf16 v[46:49], v[134:137], v[174:177], v[46:49]
	v_mfma_f32_16x16x32_bf16 v[42:45], v[142:145], v[174:177], v[42:45]
	v_mfma_f32_16x16x32_bf16 v[30:33], v[134:137], v[182:185], v[30:33]
	v_mfma_f32_16x16x32_bf16 v[26:29], v[142:145], v[182:185], v[26:29]
	v_mfma_f32_16x16x32_bf16 v[14:17], v[134:137], v[190:193], v[14:17]
	v_mfma_f32_16x16x32_bf16 v[10:13], v[142:145], v[190:193], v[10:13]
	v_mfma_f32_16x16x32_bf16 v[54:57], v[146:149], v[162:165], v[54:57]
	v_mfma_f32_16x16x32_bf16 v[50:53], v[154:157], v[162:165], v[50:53]
	v_mfma_f32_16x16x32_bf16 v[38:41], v[146:149], v[170:173], v[38:41]
	v_mfma_f32_16x16x32_bf16 v[34:37], v[154:157], v[170:173], v[34:37]
	v_mfma_f32_16x16x32_bf16 v[22:25], v[146:149], v[178:181], v[22:25]
	v_mfma_f32_16x16x32_bf16 v[18:21], v[154:157], v[178:181], v[18:21]
	v_mfma_f32_16x16x32_bf16 v[6:9], v[146:149], v[186:189], v[6:9]
	v_mfma_f32_16x16x32_bf16 v[2:5], v[154:157], v[186:189], v[2:5]
	v_mfma_f32_16x16x32_bf16 v[54:57], v[150:153], v[166:169], v[54:57]
	v_mfma_f32_16x16x32_bf16 v[50:53], v[158:161], v[166:169], v[50:53]
	v_mfma_f32_16x16x32_bf16 v[38:41], v[150:153], v[174:177], v[38:41]
	v_mfma_f32_16x16x32_bf16 v[34:37], v[158:161], v[174:177], v[34:37]
	v_mfma_f32_16x16x32_bf16 v[22:25], v[150:153], v[182:185], v[22:25]
	v_mfma_f32_16x16x32_bf16 v[18:21], v[158:161], v[182:185], v[18:21]
	v_mfma_f32_16x16x32_bf16 v[6:9], v[150:153], v[190:193], v[6:9]
	v_mfma_f32_16x16x32_bf16 v[2:5], v[158:161], v[190:193], v[2:5]
	s_barrier
; #define GAS __attribute__((address_space(1)))
;     DI void operator()(const f32x4 (&acc)[2][2][4][2], const Unit& u, int wr, int wc, int fr, int fq) const {
;         const int row0 = u.pm * BM + wr * 64 + fr, col0 = u.pn * BM + wc * 64 + 8 * fq;
;         const size_t hbase = (size_t)u.pn * ((size_t)M * 256) + wc * 64 + 8 * fq;
;         u32x4 H[2][4][2];
; #pragma unroll
;         for (int ai = 0; ai < 2; ++ai)
; #pragma unroll
;             for (int m = 0; m < 4; ++m)
; #pragma unroll
;                 for (int bj = 0; bj < 2; ++bj) H[ai][m][bj] = *(const GAS u32x4*)(hi + hbase + (size_t)(row0 + ai * HALF + m * 16) * 256 + bj * 32);
;         asm volatile("" ::: "memory");
; #pragma unroll
;         for (int ai = 0; ai < 2; ++ai) {
; #pragma unroll
;             for (int m = 0; m < 4; ++m) {
;                 const int r = row0 + ai * HALF + m * 16; const size_t off = (size_t)r * DM + col0; float ss = 0.f;
; #pragma unroll
;                 for (int bj = 0; bj < 2; ++bj) {
;                     const u32x4 h = H[ai][m][bj];
;                     const f32x4 a0 = acc[ai][bj][m][0], a1 = acc[ai][bj][m][1];
;                     float v[8];
;                     v[0] = bflo(h.x) + a0[0] * scale; v[1] = bfhi(h.x) + a0[1] * scale;
;                     v[2] = bflo(h.y) + a0[2] * scale; v[3] = bfhi(h.y) + a0[3] * scale;
;                     v[4] = bflo(h.z) + a1[0] * scale; v[5] = bfhi(h.z) + a1[1] * scale;
;                     v[6] = bflo(h.w) + a1[2] * scale; v[7] = bfhi(h.w) + a1[3] * scale;
; #pragma unroll
;                     for (int e = 0; e < 8; ++e) ss += v[e] * v[e];
;                     u32x4 nh;
;                     nh.x = cvtpk(v[0], v[1]); nh.y = cvtpk(v[2], v[3]); nh.z = cvtpk(v[4], v[5]); nh.w = cvtpk(v[6], v[7]);
;                     *(GAS u32x4*)(hi + hbase + (size_t)r * 256 + bj * 32) = nh;
; template <class Epi, class Sched, int KC, bool ALIGN_EPI = false, bool SP2 = false, bool ATILED = false>
; __device__ __forceinline__ void gemm_phase(LAS unsigned char* lds, const Gemm g, const Sched& S, const Epi& E, int wave_s) {
;     ...
;         for (int t = 0; t < nt; t += 2) {
;             const bool last = (t == nt - 2);
;             const char* a1 = cA + PG8_AOFF(t + 1);
;             const char* a2 = last ? nA : cA + PG8_AOFF(t + 2); const char* b2 = last ? nB : cB + (size_t)(t + 2) * kstep;
	s_add_i32 s48, s48, 2
	s_add_u32 s46, s46, 0x100
	s_addc_u32 s47, s47, 0
	s_add_u32 s18, s18, 0x100
	s_addc_u32 s19, s19, 0
	s_cmp_gt_u32 s48, 29
	s_cbranch_scc0 .LBB0_1021
	v_lshl_add_u32 v210, s16, 8, v228
	s_ashr_i32 s15, s14, 31
	s_lshl_b64 s[16:17], s[14:15], 23
	v_ashrrev_i32_e32 v211, 31, v210
	v_lshl_add_u64 v[130:131], v[204:205], 0, s[16:17]
	v_lshlrev_b64 v[132:133], 9, v[210:211]
	v_lshl_add_u64 v[226:227], v[130:131], 0, v[132:133]
	global_load_dwordx4 v[190:193], v[226:227], off
	global_load_dwordx4 v[186:189], v[226:227], off offset:64
	v_or_b32_e32 v132, 16, v210
	v_ashrrev_i32_e32 v133, 31, v132
	v_lshlrev_b64 v[132:133], 9, v[132:133]
	v_lshl_add_u64 v[224:225], v[130:131], 0, v[132:133]
	v_or_b32_e32 v132, 32, v210
	v_ashrrev_i32_e32 v133, 31, v132
	v_lshlrev_b64 v[132:133], 9, v[132:133]
	v_lshl_add_u64 v[222:223], v[130:131], 0, v[132:133]
	v_or_b32_e32 v132, 48, v210
	v_ashrrev_i32_e32 v133, 31, v132
	v_lshlrev_b64 v[132:133], 9, v[132:133]
	s_mov_b32 s3, 0x10000
	v_lshl_add_u64 v[220:221], v[130:131], 0, v[132:133]
	v_add_co_u32_e32 v130, vcc, s3, v226
	s_mov_b64 s[16:17], 0x10000
	s_nop 0
	v_addc_co_u32_e32 v131, vcc, 0, v227, vcc
	s_mov_b32 s3, 0x12000
	global_load_dwordx4 v[182:185], v[224:225], off
	global_load_dwordx4 v[178:181], v[224:225], off offset:64
	global_load_dwordx4 v[174:177], v[222:223], off
	global_load_dwordx4 v[170:173], v[222:223], off offset:64
	global_load_dwordx4 v[166:169], v[220:221], off
	global_load_dwordx4 v[162:165], v[220:221], off offset:64
	v_lshl_add_u64 v[218:219], v[226:227], 0, s[16:17]
	global_load_dwordx4 v[158:161], v[130:131], off
	global_load_dwordx4 v[150:153], v[218:219], off offset:64
	v_add_co_u32_e32 v130, vcc, s3, v226
	s_mov_b64 s[16:17], 0x12000
	s_nop 0
	v_addc_co_u32_e32 v131, vcc, 0, v227, vcc
	s_mov_b32 s3, 0x14000
	v_lshl_add_u64 v[216:217], v[226:227], 0, s[16:17]
	global_load_dwordx4 v[154:157], v[130:131], off
	global_load_dwordx4 v[146:149], v[216:217], off offset:64
	v_add_co_u32_e32 v130, vcc, s3, v226
	s_mov_b64 s[16:17], 0x14000
	s_nop 0
	v_addc_co_u32_e32 v131, vcc, 0, v227, vcc
	s_mov_b32 s3, 0x16000
	v_lshl_add_u64 v[214:215], v[226:227], 0, s[16:17]
	global_load_dwordx4 v[142:145], v[130:131], off
	global_load_dwordx4 v[134:137], v[214:215], off offset:64
	v_add_co_u32_e32 v130, vcc, s3, v226
	s_mov_b64 s[16:17], 0x16000
	s_nop 0
	v_addc_co_u32_e32 v131, vcc, 0, v227, vcc
	v_lshl_add_u64 v[212:213], v[226:227], 0, s[16:17]
	global_load_dwordx4 v[138:141], v[130:131], off
	s_nop 0
	global_load_dwordx4 v[130:133], v[212:213], off offset:64
	s_lshl_b32 s3, s14, 2
	s_or_b32 s14, s3, s40
	s_ashr_i32 s15, s14, 31
	s_lshl_b64 s[14:15], s[14:15], 16
	s_waitcnt vmcnt(0)
	v_lshlrev_b32_e32 v194, 16, v190
	v_and_b32_e32 v190, 0xffff0000, v190
	v_add_f32_e32 v127, v127, v190
	v_lshlrev_b32_e32 v190, 16, v191
	v_add_f32_e32 v128, v128, v190
	v_and_b32_e32 v190, 0xffff0000, v191
	v_add_f32_e32 v129, v129, v190
	v_lshlrev_b32_e32 v190, 16, v192
	v_add_f32_e32 v190, v122, v190
	v_and_b32_e32 v122, 0xffff0000, v192
	v_add_f32_e32 v191, v123, v122
	v_lshlrev_b32_e32 v122, 16, v193
	v_add_f32_e32 v126, v126, v194
	v_add_f32_e32 v192, v124, v122
	v_and_b32_e32 v122, 0xffff0000, v193
	v_mul_f32_e32 v193, v127, v127
	v_fmac_f32_e32 v193, v126, v126
	v_fmac_f32_e32 v193, v128, v128
	v_fmac_f32_e32 v193, v129, v129
	v_fmac_f32_e32 v193, v190, v190
	v_fmac_f32_e32 v193, v191, v191
	v_add_f32_e32 v125, v125, v122
	v_fmac_f32_e32 v193, v192, v192
	v_cvt_pk_bf16_f32 v122, v126, v127
	v_fmac_f32_e32 v193, v125, v125
	v_cvt_pk_bf16_f32 v123, v128, v129
	v_cvt_pk_bf16_f32 v124, v190, v191
	v_cvt_pk_bf16_f32 v125, v192, v125
	global_store_dwordx4 v[226:227], v[122:125], off
	s_nop 1
	v_lshlrev_b32_e32 v122, 16, v186
	v_add_f32_e32 v118, v118, v122
	v_and_b32_e32 v122, 0xffff0000, v186
	v_add_f32_e32 v119, v119, v122
	v_lshlrev_b32_e32 v122, 16, v187
	v_fmac_f32_e32 v193, v118, v118
	v_add_f32_e32 v120, v120, v122
	v_and_b32_e32 v122, 0xffff0000, v187
	v_fmac_f32_e32 v193, v119, v119
	v_add_f32_e32 v121, v121, v122
	v_lshlrev_b32_e32 v122, 16, v188
	v_fmac_f32_e32 v193, v120, v120
	v_add_f32_e32 v122, v114, v122
	v_and_b32_e32 v114, 0xffff0000, v188
	v_fmac_f32_e32 v193, v121, v121
	v_add_f32_e32 v123, v115, v114
	v_lshlrev_b32_e32 v114, 16, v189
	v_fmac_f32_e32 v193, v122, v122
	v_add_f32_e32 v124, v116, v114
	v_and_b32_e32 v114, 0xffff0000, v189
	v_fmac_f32_e32 v193, v123, v123
	v_add_f32_e32 v117, v117, v114
	v_fmac_f32_e32 v193, v124, v124
	v_fmac_f32_e32 v193, v117, v117
	v_cvt_pk_bf16_f32 v114, v118, v119
	v_cvt_pk_bf16_f32 v115, v120, v121
	v_cvt_pk_bf16_f32 v116, v122, v123
	v_cvt_pk_bf16_f32 v117, v124, v117
	global_store_dwordx4 v[226:227], v[114:117], off offset:64
	s_nop 1
	v_mov_b32_e32 v114, v193
	s_nop 1
	v_permlane16_swap_b32_e32 v193, v114
	v_add_f32_e32 v114, v193, v114
	v_mov_b32_e32 v115, v114
	s_nop 1
	v_permlane32_swap_b32_e32 v114, v115
	s_and_saveexec_b64 s[16:17], s[4:5]
	s_cbranch_execz .LBB0_1024
	s_add_u32 s18, s38, s14
	s_addc_u32 s19, s39, s15
	v_lshl_add_u64 v[116:117], v[210:211], 2, s[18:19]
	v_add_f32_e32 v114, v114, v115
	global_store_dword v[116:117], v114, off
